# mixer B: LDS traffic spread evenly over the step (K reads 2/slot, V reads 4-11, writes 12-13); mixer A: 3-instruction range mask for all-edge waves
# speedup vs baseline: 1.0377x; 1.0122x over previous
; __device__ __forceinline__ int crow(int i, int h) { return (i & 3) + 8 * (i >> 2) + 4 * h; }
; __device__ __forceinline__ void attnA_unit(LAS unsigned char* lds, const Args& A, int unit) {
;     ...
;                 const bool edge = (i0 < 64) || (i0 + 96 > L);
;                 float mxp[2] = {-1e30f, -1e30f};
; #pragma unroll
;                 for (int kt = 0; kt < 5; ++kt)
; #pragma unroll
;                     for (int i = 0; i < 16; ++i) {
;                         const int cr = crow(i, 0);
;                         float v = S[kt][i] * QK_C + bl[32 * kt + cr + 4 * hh - ql + 32];
;                         if (edge) { const int kidx = i0 - 64 + 32 * kt + cr + 4 * hh; if (kidx < 0 || kidx >= L) v = -1e30f; }
;                         S[kt][i] = v; mxp[i & 1] = fmaxf(mxp[i & 1], v);
;                     }
;                 float mx = fmaxf(mxp[0], mxp[1]);
.LBB0_301:
	ds_read2_b32 v[166:167], v157 offset0:32 offset1:33
	ds_read2_b32 v[168:169], v157 offset0:34 offset1:35
	v_cmp_gt_i32_e32 vcc, 64, v162
	v_cmp_lt_i32_e64 s[22:23], s99, v162
	v_add_u32_e32 v165, v162, v179
	s_or_b64 vcc, vcc, s[22:23]
	s_cmp_eq_u64 vcc, 0
	s_cbranch_scc1 .LmixA_fast
	s_cmp_eq_u64 vcc, exec
	s_cbranch_scc1 .LmixA_medium
	v_cmp_lt_i32_e64 s[22:23], -1, v165
	v_cmp_gt_i32_e64 s[24:25], s87, v165
	s_waitcnt lgkmcnt(1)
	v_fmamk_f32 v64, v64, 0x3e38aa3b, v166
	s_and_b64 s[22:23], s[22:23], s[24:25]
	v_fmac_f32_e32 v167, 0x3e38aa3b, v65
	v_add_u32_e32 v65, 1, v165
	v_cndmask_b32_e64 v166, v221, v64, s[22:23]
	v_cmp_lt_i32_e64 s[22:23], -1, v65
	v_cmp_gt_i32_e64 s[24:25], s87, v65
	v_cndmask_b32_e32 v64, v64, v166, vcc
	s_and_b64 s[22:23], s[22:23], s[24:25]
	v_add_u32_e32 v166, 2, v165
	v_cndmask_b32_e64 v65, v221, v167, s[22:23]
	v_cmp_lt_i32_e64 s[22:23], -1, v166
	v_cmp_gt_i32_e64 s[24:25], s87, v166
	s_waitcnt lgkmcnt(0)
	v_fmamk_f32 v66, v66, 0x3e38aa3b, v168
	s_and_b64 s[22:23], s[22:23], s[24:25]
	v_cndmask_b32_e64 v166, v221, v66, s[22:23]
	v_cndmask_b32_e32 v65, v167, v65, vcc
	v_cndmask_b32_e32 v66, v66, v166, vcc
	ds_read2_b32 v[166:167], v157 offset0:40 offset1:41
	v_fmac_f32_e32 v169, 0x3e38aa3b, v67
	v_add_u32_e32 v67, 3, v165
	v_cmp_lt_i32_e64 s[22:23], -1, v67
	v_cmp_gt_i32_e64 s[24:25], s87, v67
	s_and_b64 s[22:23], s[22:23], s[24:25]
	v_cndmask_b32_e64 v67, v221, v169, s[22:23]
	v_cndmask_b32_e32 v67, v169, v67, vcc
	s_mov_b32 s22, 0xf149f2ca
	ds_read2_b32 v[168:169], v157 offset0:42 offset1:43
	s_waitcnt lgkmcnt(1)
	v_fmamk_f32 v68, v68, 0x3e38aa3b, v166
	v_add_u32_e32 v166, 8, v165
	v_max3_f32 v171, v65, s22, v67
	v_cmp_lt_i32_e64 s[22:23], -1, v166
	v_cmp_gt_i32_e64 s[24:25], s87, v166
	s_and_b64 s[22:23], s[22:23], s[24:25]
	v_fmac_f32_e32 v167, 0x3e38aa3b, v69
	v_add_u32_e32 v69, 9, v165
	v_cndmask_b32_e64 v166, v221, v68, s[22:23]
	v_cmp_lt_i32_e64 s[22:23], -1, v69
	v_cmp_gt_i32_e64 s[24:25], s87, v69
	v_cndmask_b32_e32 v68, v68, v166, vcc
	s_and_b64 s[22:23], s[22:23], s[24:25]
	v_add_u32_e32 v166, 10, v165
	v_cndmask_b32_e64 v69, v221, v167, s[22:23]
	v_cmp_lt_i32_e64 s[22:23], -1, v166
	v_cmp_gt_i32_e64 s[24:25], s87, v166
	s_waitcnt lgkmcnt(0)
	v_fmamk_f32 v70, v70, 0x3e38aa3b, v168
	s_and_b64 s[22:23], s[22:23], s[24:25]
	v_cndmask_b32_e64 v166, v221, v70, s[22:23]
	v_cndmask_b32_e32 v69, v167, v69, vcc
	v_cndmask_b32_e32 v70, v70, v166, vcc
	ds_read2_b32 v[166:167], v157 offset0:48 offset1:49
	v_fmac_f32_e32 v169, 0x3e38aa3b, v71
	v_add_u32_e32 v71, 11, v165
	v_cmp_lt_i32_e64 s[22:23], -1, v71
	v_cmp_gt_i32_e64 s[24:25], s87, v71
	s_and_b64 s[22:23], s[22:23], s[24:25]
	v_cndmask_b32_e64 v71, v221, v169, s[22:23]
	v_cndmask_b32_e32 v71, v169, v71, vcc
	ds_read2_b32 v[168:169], v157 offset0:50 offset1:51
	s_waitcnt lgkmcnt(1)
	v_fmamk_f32 v72, v72, 0x3e38aa3b, v166
	v_add_u32_e32 v166, 16, v165
	v_cmp_lt_i32_e64 s[22:23], -1, v166
	v_cmp_gt_i32_e64 s[24:25], s87, v166
	s_and_b64 s[22:23], s[22:23], s[24:25]
	v_fmac_f32_e32 v167, 0x3e38aa3b, v73
	v_add_u32_e32 v73, 17, v165
	v_cndmask_b32_e64 v166, v221, v72, s[22:23]
	v_cmp_lt_i32_e64 s[22:23], -1, v73
	v_cmp_gt_i32_e64 s[24:25], s87, v73
	v_cndmask_b32_e32 v72, v72, v166, vcc
	s_and_b64 s[22:23], s[22:23], s[24:25]
	v_add_u32_e32 v166, 18, v165
	v_cndmask_b32_e64 v73, v221, v167, s[22:23]
	v_cmp_lt_i32_e64 s[22:23], -1, v166
	v_cmp_gt_i32_e64 s[24:25], s87, v166
	s_waitcnt lgkmcnt(0)
	v_fmamk_f32 v74, v74, 0x3e38aa3b, v168
	s_and_b64 s[22:23], s[22:23], s[24:25]
	v_cndmask_b32_e64 v166, v221, v74, s[22:23]
	v_cndmask_b32_e32 v73, v167, v73, vcc
	v_cndmask_b32_e32 v74, v74, v166, vcc
	ds_read2_b32 v[166:167], v157 offset0:56 offset1:57
	v_fmac_f32_e32 v169, 0x3e38aa3b, v75
	v_add_u32_e32 v75, 19, v165
	v_cmp_lt_i32_e64 s[22:23], -1, v75
	v_cmp_gt_i32_e64 s[24:25], s87, v75
	s_and_b64 s[22:23], s[22:23], s[24:25]
	v_cndmask_b32_e64 v75, v221, v169, s[22:23]
	v_cndmask_b32_e32 v168, v169, v75, vcc
	s_waitcnt lgkmcnt(0)
	v_fmamk_f32 v75, v76, 0x3e38aa3b, v166
	v_add_u32_e32 v76, 24, v165
	v_cmp_lt_i32_e64 s[22:23], -1, v76
	v_cmp_gt_i32_e64 s[24:25], s87, v76
	v_max_f32_e32 v170, 0xf149f2ca, v64
	s_and_b64 s[22:23], s[22:23], s[24:25]
	v_max3_f32 v170, v170, v66, v68
	v_cndmask_b32_e64 v76, v221, v75, s[22:23]
	v_max3_f32 v171, v171, v69, v71
	v_max3_f32 v170, v170, v70, v72
	v_cndmask_b32_e32 v75, v75, v76, vcc
	v_max3_f32 v169, v171, v73, v168
	v_max3_f32 v172, v170, v74, v75
	ds_read2_b32 v[170:171], v157 offset0:58 offset1:59
	v_add_u32_e32 v76, 25, v165
	v_cmp_lt_i32_e64 s[22:23], -1, v76
	v_cmp_gt_i32_e64 s[24:25], s87, v76
	v_fmac_f32_e32 v167, 0x3e38aa3b, v77
	s_and_b64 s[22:23], s[22:23], s[24:25]
	v_cndmask_b32_e64 v76, v221, v167, s[22:23]
	v_cndmask_b32_e32 v76, v167, v76, vcc
	ds_read2_b32 v[166:167], v157 offset0:64 offset1:65
	s_waitcnt lgkmcnt(1)
	v_fmamk_f32 v77, v78, 0x3e38aa3b, v170
	v_add_u32_e32 v78, 26, v165
	v_cmp_lt_i32_e64 s[22:23], -1, v78
	v_cmp_gt_i32_e64 s[24:25], s87, v78
	s_and_b64 s[22:23], s[22:23], s[24:25]
	v_cndmask_b32_e64 v78, v221, v77, s[22:23]
	v_cndmask_b32_e32 v77, v77, v78, vcc
	v_add_u32_e32 v78, 27, v165
	v_cmp_lt_i32_e64 s[22:23], -1, v78
	v_cmp_gt_i32_e64 s[24:25], s87, v78
	v_fmac_f32_e32 v171, 0x3e38aa3b, v79
	s_and_b64 s[22:23], s[22:23], s[24:25]
	v_cndmask_b32_e64 v78, v221, v171, s[22:23]
	s_waitcnt lgkmcnt(0)
; __device__ __forceinline__ int crow(int i, int h) { return (i & 3) + 8 * (i >> 2) + 4 * h; }
; __device__ __forceinline__ void attnA_unit(LAS unsigned char* lds, const Args& A, int unit) {
;     ...
;                 const bool edge = (i0 < 64) || (i0 + 96 > L);
;                 float mxp[2] = {-1e30f, -1e30f};
; #pragma unroll
;                 for (int kt = 0; kt < 5; ++kt)
; #pragma unroll
;                     for (int i = 0; i < 16; ++i) {
;                         const int cr = crow(i, 0);
;                         float v = S[kt][i] * QK_C + bl[32 * kt + cr + 4 * hh - ql + 32];
;                         if (edge) { const int kidx = i0 - 64 + 32 * kt + cr + 4 * hh; if (kidx < 0 || kidx >= L) v = -1e30f; }
;                         S[kt][i] = v; mxp[i & 1] = fmaxf(mxp[i & 1], v);
;                     }
;                 float mx = fmaxf(mxp[0], mxp[1]);
	v_fmamk_f32 v48, v48, 0x3e38aa3b, v166
	v_add_u32_e32 v166, 32, v165
	v_cndmask_b32_e32 v78, v171, v78, vcc
	v_cmp_lt_i32_e64 s[22:23], -1, v166
	v_cmp_gt_i32_e64 s[24:25], s87, v166
	ds_read2_b32 v[170:171], v157 offset0:66 offset1:67
	s_and_b64 s[22:23], s[22:23], s[24:25]
	v_fmac_f32_e32 v167, 0x3e38aa3b, v49
	v_add_u32_e32 v49, 33, v165
	v_cndmask_b32_e64 v166, v221, v48, s[22:23]
	v_cmp_lt_i32_e64 s[22:23], -1, v49
	v_cmp_gt_i32_e64 s[24:25], s87, v49
	v_cndmask_b32_e32 v48, v48, v166, vcc
	s_and_b64 s[22:23], s[22:23], s[24:25]
	v_add_u32_e32 v166, 34, v165
	v_cndmask_b32_e64 v49, v221, v167, s[22:23]
	v_cmp_lt_i32_e64 s[22:23], -1, v166
	v_cmp_gt_i32_e64 s[24:25], s87, v166
	s_waitcnt lgkmcnt(0)
	v_fmamk_f32 v50, v50, 0x3e38aa3b, v170
	s_and_b64 s[22:23], s[22:23], s[24:25]
	v_cndmask_b32_e64 v166, v221, v50, s[22:23]
	v_cndmask_b32_e32 v49, v167, v49, vcc
	v_cndmask_b32_e32 v50, v50, v166, vcc
	ds_read2_b32 v[166:167], v157 offset0:72 offset1:73
	v_fmac_f32_e32 v171, 0x3e38aa3b, v51
	v_add_u32_e32 v51, 35, v165
	v_cmp_lt_i32_e64 s[22:23], -1, v51
	v_cmp_gt_i32_e64 s[24:25], s87, v51
	s_and_b64 s[22:23], s[22:23], s[24:25]
	v_cndmask_b32_e64 v51, v221, v171, s[22:23]
	v_cndmask_b32_e32 v51, v171, v51, vcc
	ds_read2_b32 v[170:171], v157 offset0:74 offset1:75
	s_waitcnt lgkmcnt(1)
	v_fmamk_f32 v52, v52, 0x3e38aa3b, v166
	v_add_u32_e32 v166, 40, v165
	v_cmp_lt_i32_e64 s[22:23], -1, v166
	v_cmp_gt_i32_e64 s[24:25], s87, v166
	s_and_b64 s[22:23], s[22:23], s[24:25]
	v_fmac_f32_e32 v167, 0x3e38aa3b, v53
	v_add_u32_e32 v53, 41, v165
	v_cndmask_b32_e64 v166, v221, v52, s[22:23]
	v_cmp_lt_i32_e64 s[22:23], -1, v53
	v_cmp_gt_i32_e64 s[24:25], s87, v53
	v_cndmask_b32_e32 v52, v52, v166, vcc
	s_and_b64 s[22:23], s[22:23], s[24:25]
	v_add_u32_e32 v166, 42, v165
	v_cndmask_b32_e64 v53, v221, v167, s[22:23]
	v_cmp_lt_i32_e64 s[22:23], -1, v166
	v_cmp_gt_i32_e64 s[24:25], s87, v166
	s_waitcnt lgkmcnt(0)
	v_fmamk_f32 v54, v54, 0x3e38aa3b, v170
	s_and_b64 s[22:23], s[22:23], s[24:25]
	v_cndmask_b32_e64 v166, v221, v54, s[22:23]
	v_cndmask_b32_e32 v53, v167, v53, vcc
	v_cndmask_b32_e32 v54, v54, v166, vcc
	ds_read2_b32 v[166:167], v157 offset0:80 offset1:81
	v_fmac_f32_e32 v171, 0x3e38aa3b, v55
	v_add_u32_e32 v55, 43, v165
	v_cmp_lt_i32_e64 s[22:23], -1, v55
	v_cmp_gt_i32_e64 s[24:25], s87, v55
	s_and_b64 s[22:23], s[22:23], s[24:25]
	v_cndmask_b32_e64 v55, v221, v171, s[22:23]
	v_cndmask_b32_e32 v55, v171, v55, vcc
	ds_read2_b32 v[170:171], v157 offset0:82 offset1:83
	s_waitcnt lgkmcnt(1)
	v_fmamk_f32 v56, v56, 0x3e38aa3b, v166
	v_add_u32_e32 v166, 48, v165
	v_cmp_lt_i32_e64 s[22:23], -1, v166
	v_cmp_gt_i32_e64 s[24:25], s87, v166
	s_and_b64 s[22:23], s[22:23], s[24:25]
	v_fmac_f32_e32 v167, 0x3e38aa3b, v57
	v_add_u32_e32 v57, 49, v165
	v_cndmask_b32_e64 v166, v221, v56, s[22:23]
	v_cmp_lt_i32_e64 s[22:23], -1, v57
	v_cmp_gt_i32_e64 s[24:25], s87, v57
	v_cndmask_b32_e32 v56, v56, v166, vcc
	s_and_b64 s[22:23], s[22:23], s[24:25]
	v_add_u32_e32 v166, 50, v165
	v_cndmask_b32_e64 v57, v221, v167, s[22:23]
	v_cmp_lt_i32_e64 s[22:23], -1, v166
	v_cmp_gt_i32_e64 s[24:25], s87, v166
	s_waitcnt lgkmcnt(0)
	v_fmamk_f32 v58, v58, 0x3e38aa3b, v170
	s_and_b64 s[22:23], s[22:23], s[24:25]
	v_cndmask_b32_e64 v166, v221, v58, s[22:23]
	v_cndmask_b32_e32 v57, v167, v57, vcc
	v_cndmask_b32_e32 v58, v58, v166, vcc
	ds_read2_b32 v[166:167], v157 offset0:88 offset1:89
	v_fmac_f32_e32 v171, 0x3e38aa3b, v59
	v_add_u32_e32 v59, 51, v165
	v_cmp_lt_i32_e64 s[22:23], -1, v59
	v_cmp_gt_i32_e64 s[24:25], s87, v59
	s_and_b64 s[22:23], s[22:23], s[24:25]
	v_cndmask_b32_e64 v59, v221, v171, s[22:23]
	v_cndmask_b32_e32 v59, v171, v59, vcc
	ds_read2_b32 v[170:171], v157 offset0:90 offset1:91
	s_waitcnt lgkmcnt(1)
	v_fmamk_f32 v60, v60, 0x3e38aa3b, v166
	v_add_u32_e32 v166, 56, v165
	v_cmp_lt_i32_e64 s[22:23], -1, v166
	v_cmp_gt_i32_e64 s[24:25], s87, v166
	s_and_b64 s[22:23], s[22:23], s[24:25]
	v_fmac_f32_e32 v167, 0x3e38aa3b, v61
	v_add_u32_e32 v61, 57, v165
	v_cndmask_b32_e64 v166, v221, v60, s[22:23]
	v_cmp_lt_i32_e64 s[22:23], -1, v61
	v_cmp_gt_i32_e64 s[24:25], s87, v61
	s_and_b64 s[22:23], s[22:23], s[24:25]
	v_cndmask_b32_e64 v61, v221, v167, s[22:23]
	v_cndmask_b32_e32 v61, v167, v61, vcc
	v_add_u32_e32 v167, 58, v165
	v_max3_f32 v79, v169, v76, v78
	v_max3_f32 v169, v172, v77, v48
	v_cmp_lt_i32_e64 s[22:23], -1, v167
	v_cmp_gt_i32_e64 s[24:25], s87, v167
	v_max3_f32 v169, v169, v50, v52
	s_waitcnt lgkmcnt(0)
	v_fmamk_f32 v62, v62, 0x3e38aa3b, v170
	s_and_b64 s[22:23], s[22:23], s[24:25]
	v_max3_f32 v169, v169, v54, v56
	v_cndmask_b32_e32 v60, v60, v166, vcc
	v_cndmask_b32_e64 v167, v221, v62, s[22:23]
	v_max3_f32 v166, v169, v58, v60
	v_cndmask_b32_e32 v169, v62, v167, vcc
	v_add_u32_e32 v62, 59, v165
	v_fmac_f32_e32 v171, 0x3e38aa3b, v63
	v_cmp_lt_i32_e64 s[22:23], -1, v62
	v_cmp_gt_i32_e64 s[24:25], s87, v62
	ds_read2_b32 v[62:63], v157 offset0:96 offset1:97
	s_and_b64 s[22:23], s[22:23], s[24:25]
	v_cndmask_b32_e64 v167, v221, v171, s[22:23]
	v_cndmask_b32_e32 v208, v171, v167, vcc
	v_max3_f32 v79, v79, v49, v51
	s_waitcnt lgkmcnt(0)
	v_fmamk_f32 v32, v32, 0x3e38aa3b, v62
	v_add_u32_e32 v62, 64, v165
	v_cmp_lt_i32_e64 s[22:23], -1, v62
	v_cmp_gt_i32_e64 s[24:25], s87, v62
	s_and_b64 s[22:23], s[22:23], s[24:25]
	v_cndmask_b32_e64 v62, v221, v32, s[22:23]
	v_cndmask_b32_e32 v209, v32, v62, vcc
	v_max3_f32 v32, v166, v169, v209
	ds_read2_b32 v[166:167], v157 offset0:98 offset1:99
	v_fmac_f32_e32 v63, 0x3e38aa3b, v33
	v_add_u32_e32 v33, 0x41, v165
	v_cmp_lt_i32_e64 s[22:23], -1, v33
	v_cmp_gt_i32_e64 s[24:25], s87, v33
	s_and_b64 s[22:23], s[22:23], s[24:25]
	v_cndmask_b32_e64 v33, v221, v63, s[22:23]
	v_cndmask_b32_e32 v210, v63, v33, vcc
	ds_read2_b32 v[62:63], v157 offset0:104 offset1:105
	s_waitcnt lgkmcnt(1)
; __device__ __forceinline__ int crow(int i, int h) { return (i & 3) + 8 * (i >> 2) + 4 * h; }
; __device__ __forceinline__ void attnA_unit(LAS unsigned char* lds, const Args& A, int unit) {
;     ...
;                 const bool edge = (i0 < 64) || (i0 + 96 > L);
;                 float mxp[2] = {-1e30f, -1e30f};
; #pragma unroll
;                 for (int kt = 0; kt < 5; ++kt)
; #pragma unroll
;                     for (int i = 0; i < 16; ++i) {
;                         const int cr = crow(i, 0);
;                         float v = S[kt][i] * QK_C + bl[32 * kt + cr + 4 * hh - ql + 32];
;                         if (edge) { const int kidx = i0 - 64 + 32 * kt + cr + 4 * hh; if (kidx < 0 || kidx >= L) v = -1e30f; }
;                         S[kt][i] = v; mxp[i & 1] = fmaxf(mxp[i & 1], v);
;                     }
;                 float mx = fmaxf(mxp[0], mxp[1]);
	v_fmamk_f32 v33, v34, 0x3e38aa3b, v166
	v_add_u32_e32 v34, 0x42, v165
	v_cmp_lt_i32_e64 s[22:23], -1, v34
	v_cmp_gt_i32_e64 s[24:25], s87, v34
	s_and_b64 s[22:23], s[22:23], s[24:25]
	v_cndmask_b32_e64 v34, v221, v33, s[22:23]
	v_cndmask_b32_e32 v33, v33, v34, vcc
	v_add_u32_e32 v34, 0x43, v165
	v_cmp_lt_i32_e64 s[22:23], -1, v34
	v_cmp_gt_i32_e64 s[24:25], s87, v34
	v_fmac_f32_e32 v167, 0x3e38aa3b, v35
	s_and_b64 s[22:23], s[22:23], s[24:25]
	s_waitcnt lgkmcnt(0)
	v_fmamk_f32 v35, v36, 0x3e38aa3b, v62
	v_add_u32_e32 v36, 0x48, v165
	v_cndmask_b32_e64 v34, v221, v167, s[22:23]
	v_cmp_lt_i32_e64 s[22:23], -1, v36
	v_cmp_gt_i32_e64 s[24:25], s87, v36
	s_and_b64 s[22:23], s[22:23], s[24:25]
	v_cndmask_b32_e32 v34, v167, v34, vcc
	v_cndmask_b32_e64 v36, v221, v35, s[22:23]
	ds_read2_b32 v[166:167], v157 offset0:106 offset1:107
	v_cndmask_b32_e32 v35, v35, v36, vcc
	v_add_u32_e32 v36, 0x49, v165
	v_cmp_lt_i32_e64 s[22:23], -1, v36
	v_cmp_gt_i32_e64 s[24:25], s87, v36
	v_fmac_f32_e32 v63, 0x3e38aa3b, v37
	s_and_b64 s[22:23], s[22:23], s[24:25]
	v_cndmask_b32_e64 v36, v221, v63, s[22:23]
	v_cndmask_b32_e32 v36, v63, v36, vcc
	ds_read2_b32 v[62:63], v157 offset0:112 offset1:113
	s_waitcnt lgkmcnt(1)
	v_fmamk_f32 v37, v38, 0x3e38aa3b, v166
	v_add_u32_e32 v38, 0x4a, v165
	v_cmp_lt_i32_e64 s[22:23], -1, v38
	v_cmp_gt_i32_e64 s[24:25], s87, v38
	s_and_b64 s[22:23], s[22:23], s[24:25]
	v_cndmask_b32_e64 v38, v221, v37, s[22:23]
	v_cndmask_b32_e32 v37, v37, v38, vcc
	v_add_u32_e32 v38, 0x4b, v165
	v_cmp_lt_i32_e64 s[22:23], -1, v38
	v_cmp_gt_i32_e64 s[24:25], s87, v38
	v_fmac_f32_e32 v167, 0x3e38aa3b, v39
	s_and_b64 s[22:23], s[22:23], s[24:25]
	s_waitcnt lgkmcnt(0)
	v_fmamk_f32 v39, v40, 0x3e38aa3b, v62
	v_add_u32_e32 v40, 0x50, v165
	v_cndmask_b32_e64 v38, v221, v167, s[22:23]
	v_cmp_lt_i32_e64 s[22:23], -1, v40
	v_cmp_gt_i32_e64 s[24:25], s87, v40
	s_and_b64 s[22:23], s[22:23], s[24:25]
	v_cndmask_b32_e32 v38, v167, v38, vcc
	v_cndmask_b32_e64 v40, v221, v39, s[22:23]
	ds_read2_b32 v[166:167], v157 offset0:114 offset1:115
	v_cndmask_b32_e32 v39, v39, v40, vcc
	v_add_u32_e32 v40, 0x51, v165
	v_cmp_lt_i32_e64 s[22:23], -1, v40
	v_cmp_gt_i32_e64 s[24:25], s87, v40
	v_fmac_f32_e32 v63, 0x3e38aa3b, v41
	s_and_b64 s[22:23], s[22:23], s[24:25]
	v_cndmask_b32_e64 v40, v221, v63, s[22:23]
	v_cndmask_b32_e32 v40, v63, v40, vcc
	ds_read2_b32 v[62:63], v157 offset0:120 offset1:121
	s_waitcnt lgkmcnt(1)
	v_fmamk_f32 v41, v42, 0x3e38aa3b, v166
	v_add_u32_e32 v42, 0x52, v165
	v_cmp_lt_i32_e64 s[22:23], -1, v42
	v_cmp_gt_i32_e64 s[24:25], s87, v42
	s_and_b64 s[22:23], s[22:23], s[24:25]
	v_cndmask_b32_e64 v42, v221, v41, s[22:23]
	v_cndmask_b32_e32 v41, v41, v42, vcc
	v_add_u32_e32 v42, 0x53, v165
	v_cmp_lt_i32_e64 s[22:23], -1, v42
	v_cmp_gt_i32_e64 s[24:25], s87, v42
	v_fmac_f32_e32 v167, 0x3e38aa3b, v43
	s_and_b64 s[22:23], s[22:23], s[24:25]
	s_waitcnt lgkmcnt(0)
	v_fmamk_f32 v43, v44, 0x3e38aa3b, v62
	v_add_u32_e32 v44, 0x58, v165
	v_cndmask_b32_e64 v42, v221, v167, s[22:23]
	v_cmp_lt_i32_e64 s[22:23], -1, v44
	v_cmp_gt_i32_e64 s[24:25], s87, v44
	s_and_b64 s[22:23], s[22:23], s[24:25]
	v_cndmask_b32_e32 v42, v167, v42, vcc
	v_cndmask_b32_e64 v44, v221, v43, s[22:23]
	ds_read2_b32 v[166:167], v157 offset0:122 offset1:123
	v_cndmask_b32_e32 v43, v43, v44, vcc
	v_add_u32_e32 v44, 0x59, v165
	v_cmp_lt_i32_e64 s[22:23], -1, v44
	v_cmp_gt_i32_e64 s[24:25], s87, v44
	v_fmac_f32_e32 v63, 0x3e38aa3b, v45
	s_and_b64 s[22:23], s[22:23], s[24:25]
	v_cndmask_b32_e64 v44, v221, v63, s[22:23]
	v_cndmask_b32_e32 v44, v63, v44, vcc
	ds_read2_b32 v[62:63], v157 offset0:128 offset1:129
	s_waitcnt lgkmcnt(1)
	v_fmamk_f32 v45, v46, 0x3e38aa3b, v166
	v_add_u32_e32 v46, 0x5a, v165
	v_cmp_lt_i32_e64 s[22:23], -1, v46
	v_cmp_gt_i32_e64 s[24:25], s87, v46
	s_and_b64 s[22:23], s[22:23], s[24:25]
	v_cndmask_b32_e64 v46, v221, v45, s[22:23]
	v_cndmask_b32_e32 v45, v45, v46, vcc
	v_add_u32_e32 v46, 0x5b, v165
	v_cmp_lt_i32_e64 s[22:23], -1, v46
	v_cmp_gt_i32_e64 s[24:25], s87, v46
	v_fmac_f32_e32 v167, 0x3e38aa3b, v47
	s_and_b64 s[22:23], s[22:23], s[24:25]
	v_cndmask_b32_e64 v46, v221, v167, s[22:23]
	s_waitcnt lgkmcnt(0)
	v_fmamk_f32 v16, v16, 0x3e38aa3b, v62
	v_add_u32_e32 v62, 0x60, v165
	v_cndmask_b32_e32 v46, v167, v46, vcc
	v_cmp_lt_i32_e64 s[22:23], -1, v62
	v_cmp_gt_i32_e64 s[24:25], s87, v62
	ds_read2_b32 v[166:167], v157 offset0:130 offset1:131
	s_and_b64 s[22:23], s[22:23], s[24:25]
	v_fmac_f32_e32 v63, 0x3e38aa3b, v17
	v_add_u32_e32 v17, 0x61, v165
	v_cndmask_b32_e64 v62, v221, v16, s[22:23]
	v_cmp_lt_i32_e64 s[22:23], -1, v17
	v_cmp_gt_i32_e64 s[24:25], s87, v17
	v_max3_f32 v79, v79, v53, v55
	v_cndmask_b32_e32 v16, v16, v62, vcc
	s_and_b64 s[22:23], s[22:23], s[24:25]
	v_add_u32_e32 v62, 0x62, v165
	v_max3_f32 v79, v79, v57, v59
	v_cndmask_b32_e64 v17, v221, v63, s[22:23]
	v_cmp_lt_i32_e64 s[22:23], -1, v62
	v_cmp_gt_i32_e64 s[24:25], s87, v62
	v_max3_f32 v79, v79, v61, v208
	s_waitcnt lgkmcnt(0)
	v_fmamk_f32 v18, v18, 0x3e38aa3b, v166
	s_and_b64 s[22:23], s[22:23], s[24:25]
	v_fmac_f32_e32 v167, 0x3e38aa3b, v19
	v_add_u32_e32 v19, 0x63, v165
	v_max3_f32 v79, v79, v210, v34
	v_cndmask_b32_e64 v62, v221, v18, s[22:23]
	v_cmp_lt_i32_e64 s[22:23], -1, v19
	v_cmp_gt_i32_e64 s[24:25], s87, v19
	v_max3_f32 v79, v79, v36, v38
	v_cndmask_b32_e32 v17, v63, v17, vcc
	v_cndmask_b32_e32 v18, v18, v62, vcc
	ds_read2_b32 v[62:63], v157 offset0:136 offset1:137
	s_and_b64 s[22:23], s[22:23], s[24:25]
	v_max3_f32 v79, v79, v40, v42
	v_cndmask_b32_e64 v19, v221, v167, s[22:23]
	v_max3_f32 v47, v79, v44, v46
	v_cndmask_b32_e32 v19, v167, v19, vcc
	v_max3_f32 v79, v47, v17, v19
	v_add_u32_e32 v47, 0x68, v165
	v_cmp_lt_i32_e64 s[22:23], -1, v47
	v_cmp_gt_i32_e64 s[24:25], s87, v47
	ds_read2_b32 v[166:167], v157 offset0:138 offset1:139
	s_waitcnt lgkmcnt(1)
; __device__ __forceinline__ int crow(int i, int h) { return (i & 3) + 8 * (i >> 2) + 4 * h; }
; __device__ __forceinline__ void attnA_unit(LAS unsigned char* lds, const Args& A, int unit) {
;     ...
;                 const bool edge = (i0 < 64) || (i0 + 96 > L);
;                 float mxp[2] = {-1e30f, -1e30f};
; #pragma unroll
;                 for (int kt = 0; kt < 5; ++kt)
; #pragma unroll
;                     for (int i = 0; i < 16; ++i) {
;                         const int cr = crow(i, 0);
;                         float v = S[kt][i] * QK_C + bl[32 * kt + cr + 4 * hh - ql + 32];
;                         if (edge) { const int kidx = i0 - 64 + 32 * kt + cr + 4 * hh; if (kidx < 0 || kidx >= L) v = -1e30f; }
;                         S[kt][i] = v; mxp[i & 1] = fmaxf(mxp[i & 1], v);
;                     }
;                 float mx = fmaxf(mxp[0], mxp[1]);
	v_fmamk_f32 v20, v20, 0x3e38aa3b, v62
	s_and_b64 s[22:23], s[22:23], s[24:25]
	v_fmac_f32_e32 v63, 0x3e38aa3b, v21
	v_add_u32_e32 v21, 0x69, v165
	v_cndmask_b32_e64 v47, v221, v20, s[22:23]
	v_cmp_lt_i32_e64 s[22:23], -1, v21
	v_cmp_gt_i32_e64 s[24:25], s87, v21
	s_and_b64 s[22:23], s[22:23], s[24:25]
	v_cndmask_b32_e64 v21, v221, v63, s[22:23]
	v_cndmask_b32_e32 v20, v20, v47, vcc
	v_cndmask_b32_e32 v47, v63, v21, vcc
	s_waitcnt lgkmcnt(0)
	v_fmamk_f32 v21, v22, 0x3e38aa3b, v166
	v_add_u32_e32 v22, 0x6a, v165
	v_cmp_lt_i32_e64 s[22:23], -1, v22
	v_cmp_gt_i32_e64 s[24:25], s87, v22
	s_and_b64 s[22:23], s[22:23], s[24:25]
	v_cndmask_b32_e64 v22, v221, v21, s[22:23]
	ds_read2_b32 v[62:63], v157 offset0:144 offset1:145
	v_cndmask_b32_e32 v211, v21, v22, vcc
	v_add_u32_e32 v21, 0x6b, v165
	v_cmp_lt_i32_e64 s[22:23], -1, v21
	v_cmp_gt_i32_e64 s[24:25], s87, v21
	v_fmac_f32_e32 v167, 0x3e38aa3b, v23
	s_and_b64 s[22:23], s[22:23], s[24:25]
	v_cndmask_b32_e64 v21, v221, v167, s[22:23]
	v_cndmask_b32_e32 v23, v167, v21, vcc
	ds_read2_b32 v[166:167], v157 offset0:146 offset1:147
	s_waitcnt lgkmcnt(1)
	v_fmamk_f32 v22, v24, 0x3e38aa3b, v62
	v_add_u32_e32 v24, 0x70, v165
	v_cmp_lt_i32_e64 s[22:23], -1, v24
	v_cmp_gt_i32_e64 s[24:25], s87, v24
	s_and_b64 s[22:23], s[22:23], s[24:25]
	v_cndmask_b32_e64 v24, v221, v22, s[22:23]
	v_cndmask_b32_e32 v22, v22, v24, vcc
	v_add_u32_e32 v24, 0x71, v165
	v_cmp_lt_i32_e64 s[22:23], -1, v24
	v_cmp_gt_i32_e64 s[24:25], s87, v24
	v_fmac_f32_e32 v63, 0x3e38aa3b, v25
	s_and_b64 s[22:23], s[22:23], s[24:25]
	s_waitcnt lgkmcnt(0)
	v_fmamk_f32 v25, v26, 0x3e38aa3b, v166
	v_add_u32_e32 v26, 0x72, v165
	v_cndmask_b32_e64 v24, v221, v63, s[22:23]
	v_cmp_lt_i32_e64 s[22:23], -1, v26
	v_cmp_gt_i32_e64 s[24:25], s87, v26
	s_and_b64 s[22:23], s[22:23], s[24:25]
	v_cndmask_b32_e64 v26, v221, v25, s[22:23]
	v_cndmask_b32_e32 v24, v63, v24, vcc
	v_cndmask_b32_e32 v25, v25, v26, vcc
	v_add_u32_e32 v26, 0x73, v165
	ds_read2_b32 v[62:63], v157 offset0:152 offset1:153
	v_cmp_lt_i32_e64 s[22:23], -1, v26
	v_cmp_gt_i32_e64 s[24:25], s87, v26
	v_fmac_f32_e32 v167, 0x3e38aa3b, v27
	s_and_b64 s[22:23], s[22:23], s[24:25]
	v_cndmask_b32_e64 v26, v221, v167, s[22:23]
	v_max3_f32 v21, v79, v47, v23
	v_cndmask_b32_e32 v27, v167, v26, vcc
	v_add_u32_e32 v26, 0x78, v165
	v_max3_f32 v79, v21, v24, v27
	s_waitcnt lgkmcnt(0)
	v_fmamk_f32 v21, v28, 0x3e38aa3b, v62
	v_cmp_lt_i32_e64 s[22:23], -1, v26
	v_cmp_gt_i32_e64 s[24:25], s87, v26
	v_fmac_f32_e32 v63, 0x3e38aa3b, v29
	ds_read2_b32 v[28:29], v157 offset0:154 offset1:155
	s_and_b64 s[22:23], s[22:23], s[24:25]
	v_cndmask_b32_e64 v26, v221, v21, s[22:23]
	v_cndmask_b32_e32 v21, v21, v26, vcc
	v_add_u32_e32 v26, 0x79, v165
	v_cmp_lt_i32_e64 s[22:23], -1, v26
	v_cmp_gt_i32_e64 s[24:25], s87, v26
	s_and_b64 s[22:23], s[22:23], s[24:25]
	s_waitcnt lgkmcnt(0)
	v_fmamk_f32 v28, v30, 0x3e38aa3b, v28
	v_add_u32_e32 v30, 0x7a, v165
	v_cndmask_b32_e64 v26, v221, v63, s[22:23]
	v_cmp_lt_i32_e64 s[22:23], -1, v30
	v_cmp_gt_i32_e64 s[24:25], s87, v30
	s_and_b64 s[22:23], s[22:23], s[24:25]
	v_cndmask_b32_e64 v30, v221, v28, s[22:23]
	v_cndmask_b32_e32 v28, v28, v30, vcc
	v_add_u32_e32 v30, 0x7b, v165
	v_fmac_f32_e32 v29, 0x3e38aa3b, v31
	v_cmp_lt_i32_e64 s[22:23], -1, v30
	v_cmp_gt_i32_e64 s[24:25], s87, v30
	ds_read2_b32 v[30:31], v157 offset0:160 offset1:161
	v_max3_f32 v32, v32, v33, v35
	s_and_b64 s[22:23], s[22:23], s[24:25]
	v_max3_f32 v32, v32, v37, v39
	v_cndmask_b32_e64 v62, v221, v29, s[22:23]
	s_waitcnt lgkmcnt(0)
	v_fmamk_f32 v0, v0, 0x3e38aa3b, v30
	v_add_u32_e32 v30, 0x80, v165
	v_cmp_lt_i32_e64 s[22:23], -1, v30
	v_cmp_gt_i32_e64 s[24:25], s87, v30
	v_max3_f32 v32, v32, v41, v43
	s_and_b64 s[22:23], s[22:23], s[24:25]
	v_max3_f32 v32, v32, v45, v16
	v_cndmask_b32_e64 v30, v221, v0, s[22:23]
	v_max3_f32 v32, v32, v18, v20
	v_cndmask_b32_e32 v223, v0, v30, vcc
	v_fmac_f32_e32 v31, 0x3e38aa3b, v1
	ds_read2_b32 v[0:1], v157 offset0:162 offset1:163
	v_max3_f32 v32, v32, v211, v22
	v_max3_f32 v32, v32, v25, v21
	v_max3_f32 v30, v32, v28, v223
	v_add_u32_e32 v32, 0x81, v165
	v_cmp_lt_i32_e64 s[22:23], -1, v32
	v_cmp_gt_i32_e64 s[24:25], s87, v32
	s_and_b64 s[22:23], s[22:23], s[24:25]
	s_waitcnt lgkmcnt(0)
	v_fmamk_f32 v0, v2, 0x3e38aa3b, v0
	v_add_u32_e32 v2, 0x82, v165
	v_cndmask_b32_e64 v32, v221, v31, s[22:23]
	v_cmp_lt_i32_e64 s[22:23], -1, v2
	v_cmp_gt_i32_e64 s[24:25], s87, v2
	s_and_b64 s[22:23], s[22:23], s[24:25]
	v_cndmask_b32_e64 v2, v221, v0, s[22:23]
	v_cndmask_b32_e32 v225, v0, v2, vcc
	v_add_u32_e32 v0, 0x83, v165
	v_fmac_f32_e32 v1, 0x3e38aa3b, v3
	v_cmp_lt_i32_e64 s[22:23], -1, v0
	v_cmp_gt_i32_e64 s[24:25], s87, v0
	ds_read2_b32 v[2:3], v157 offset0:168 offset1:169
	s_and_b64 s[22:23], s[22:23], s[24:25]
	v_cndmask_b32_e64 v0, v221, v1, s[22:23]
	v_cndmask_b32_e32 v227, v1, v0, vcc
	v_add_u32_e32 v1, 0x88, v165
	v_cmp_lt_i32_e64 s[22:23], -1, v1
	v_cmp_gt_i32_e64 s[24:25], s87, v1
	s_waitcnt lgkmcnt(0)
	v_fmamk_f32 v0, v4, 0x3e38aa3b, v2
	s_and_b64 s[22:23], s[22:23], s[24:25]
	v_cndmask_b32_e64 v1, v221, v0, s[22:23]
	v_add_u32_e32 v2, 0x89, v165
	v_cndmask_b32_e32 v228, v0, v1, vcc
	v_cmp_lt_i32_e64 s[22:23], -1, v2
	ds_read2_b32 v[0:1], v157 offset0:170 offset1:171
	v_cmp_gt_i32_e64 s[24:25], s87, v2
	v_fmac_f32_e32 v3, 0x3e38aa3b, v5
	s_and_b64 s[22:23], s[22:23], s[24:25]
	v_cndmask_b32_e64 v2, v221, v3, s[22:23]
	v_cndmask_b32_e32 v230, v3, v2, vcc
	v_add_u32_e32 v2, 0x8a, v165
	v_cmp_lt_i32_e64 s[22:23], -1, v2
	v_cmp_gt_i32_e64 s[24:25], s87, v2
	s_waitcnt lgkmcnt(0)
; __device__ __forceinline__ int crow(int i, int h) { return (i & 3) + 8 * (i >> 2) + 4 * h; }
; __device__ __forceinline__ void attnA_unit(LAS unsigned char* lds, const Args& A, int unit) {
;     ...
;                 const bool edge = (i0 < 64) || (i0 + 96 > L);
;                 float mxp[2] = {-1e30f, -1e30f};
; #pragma unroll
;                 for (int kt = 0; kt < 5; ++kt)
; #pragma unroll
;                     for (int i = 0; i < 16; ++i) {
;                         const int cr = crow(i, 0);
;                         float v = S[kt][i] * QK_C + bl[32 * kt + cr + 4 * hh - ql + 32];
;                         if (edge) { const int kidx = i0 - 64 + 32 * kt + cr + 4 * hh; if (kidx < 0 || kidx >= L) v = -1e30f; }
;                         S[kt][i] = v; mxp[i & 1] = fmaxf(mxp[i & 1], v);
;                     }
;                 float mx = fmaxf(mxp[0], mxp[1]);
	v_fmamk_f32 v0, v6, 0x3e38aa3b, v0
	s_and_b64 s[22:23], s[22:23], s[24:25]
	v_cndmask_b32_e64 v2, v221, v0, s[22:23]
	v_cndmask_b32_e32 v232, v0, v2, vcc
	v_add_u32_e32 v0, 0x8b, v165
	v_cmp_lt_i32_e64 s[22:23], -1, v0
	v_cmp_gt_i32_e64 s[24:25], s87, v0
	ds_read2_b32 v[2:3], v157 offset0:176 offset1:177
	v_fmac_f32_e32 v1, 0x3e38aa3b, v7
	s_and_b64 s[22:23], s[22:23], s[24:25]
	v_cndmask_b32_e64 v0, v221, v1, s[22:23]
	v_cndmask_b32_e32 v233, v1, v0, vcc
	v_add_u32_e32 v1, 0x90, v165
	v_cmp_lt_i32_e64 s[22:23], -1, v1
	v_cmp_gt_i32_e64 s[24:25], s87, v1
	s_waitcnt lgkmcnt(0)
	v_fmamk_f32 v0, v8, 0x3e38aa3b, v2
	s_and_b64 s[22:23], s[22:23], s[24:25]
	v_cndmask_b32_e64 v1, v221, v0, s[22:23]
	v_add_u32_e32 v2, 0x91, v165
	v_cndmask_b32_e32 v231, v0, v1, vcc
	v_cmp_lt_i32_e64 s[22:23], -1, v2
	ds_read2_b32 v[0:1], v157 offset0:178 offset1:179
	v_cmp_gt_i32_e64 s[24:25], s87, v2
	v_fmac_f32_e32 v3, 0x3e38aa3b, v9
	s_and_b64 s[22:23], s[22:23], s[24:25]
	v_cndmask_b32_e64 v2, v221, v3, s[22:23]
	v_cndmask_b32_e32 v234, v3, v2, vcc
	v_add_u32_e32 v2, 0x92, v165
	v_cmp_lt_i32_e64 s[22:23], -1, v2
	v_cmp_gt_i32_e64 s[24:25], s87, v2
	s_waitcnt lgkmcnt(0)
	v_fmamk_f32 v0, v10, 0x3e38aa3b, v0
	s_and_b64 s[22:23], s[22:23], s[24:25]
	v_cndmask_b32_e64 v2, v221, v0, s[22:23]
	v_cndmask_b32_e32 v235, v0, v2, vcc
	v_add_u32_e32 v0, 0x93, v165
	v_cmp_lt_i32_e64 s[22:23], -1, v0
	v_cmp_gt_i32_e64 s[24:25], s87, v0
	ds_read2_b32 v[2:3], v157 offset0:184 offset1:185
	v_fmac_f32_e32 v1, 0x3e38aa3b, v11
	s_and_b64 s[22:23], s[22:23], s[24:25]
	v_cndmask_b32_e64 v0, v221, v1, s[22:23]
	v_cndmask_b32_e32 v236, v1, v0, vcc
	v_add_u32_e32 v1, 0x98, v165
	v_cmp_lt_i32_e64 s[22:23], -1, v1
	v_cmp_gt_i32_e64 s[24:25], s87, v1
	s_waitcnt lgkmcnt(0)
	v_fmamk_f32 v0, v12, 0x3e38aa3b, v2
	s_and_b64 s[22:23], s[22:23], s[24:25]
	v_max3_f32 v4, v30, v225, v228
	v_cndmask_b32_e64 v1, v221, v0, s[22:23]
	v_max3_f32 v4, v4, v232, v231
	v_cndmask_b32_e32 v237, v0, v1, vcc
	v_max3_f32 v2, v4, v235, v237
	v_add_u32_e32 v4, 0x99, v165
	v_cmp_lt_i32_e64 s[22:23], -1, v4
	ds_read2_b32 v[0:1], v157 offset0:186 offset1:187
	v_cmp_gt_i32_e64 s[24:25], s87, v4
	v_fmac_f32_e32 v3, 0x3e38aa3b, v13
	s_and_b64 s[22:23], s[22:23], s[24:25]
	v_cndmask_b32_e64 v4, v221, v3, s[22:23]
	v_cndmask_b32_e32 v240, v3, v4, vcc
	v_add_u32_e32 v3, 0x9a, v165
	v_cmp_lt_i32_e64 s[22:23], -1, v3
	v_cmp_gt_i32_e64 s[24:25], s87, v3
	s_waitcnt lgkmcnt(0)
	v_fmamk_f32 v0, v14, 0x3e38aa3b, v0
	s_and_b64 s[22:23], s[22:23], s[24:25]
	v_cndmask_b32_e64 v3, v221, v0, s[22:23]
	v_cndmask_b32_e32 v26, v63, v26, vcc
	v_cndmask_b32_e32 v224, v29, v62, vcc
	v_cndmask_b32_e32 v239, v0, v3, vcc
	v_add_u32_e32 v0, 0x9b, v165
	v_max3_f32 v29, v79, v26, v224
	v_cndmask_b32_e32 v226, v31, v32, vcc
	v_cmp_lt_i32_e64 s[22:23], -1, v0
	v_cmp_gt_i32_e64 s[24:25], s87, v0
	v_max3_f32 v29, v29, v226, v227
	v_fmac_f32_e32 v1, 0x3e38aa3b, v15
	s_and_b64 s[22:23], s[22:23], s[24:25]
	v_max3_f32 v5, v29, v230, v233
	v_cndmask_b32_e64 v0, v221, v1, s[22:23]
	v_max3_f32 v5, v5, v234, v236
	v_cndmask_b32_e32 v241, v1, v0, vcc
	v_max3_f32 v0, v5, v240, v241
	v_max3_f32 v0, v2, v239, v0
	s_branch .LmixA_join
.LmixA_medium:
	v_cmp_gt_u32_e64 s[22:23], s87, v165
	s_waitcnt lgkmcnt(1)
	v_fmamk_f32 v64, v64, 0x3e38aa3b, v166
	v_fmac_f32_e32 v167, 0x3e38aa3b, v65
	v_add_u32_e32 v65, 1, v165
	v_cndmask_b32_e64 v166, v221, v64, s[22:23]
	v_cmp_gt_u32_e64 s[22:23], s87, v65
	v_mov_b32_e32 v64, v166
	v_add_u32_e32 v166, 2, v165
	v_cndmask_b32_e64 v65, v221, v167, s[22:23]
	v_cmp_gt_u32_e64 s[22:23], s87, v166
	s_waitcnt lgkmcnt(0)
	v_fmamk_f32 v66, v66, 0x3e38aa3b, v168
	v_cndmask_b32_e64 v166, v221, v66, s[22:23]
	v_mov_b32_e32 v66, v166
	ds_read2_b32 v[166:167], v157 offset0:40 offset1:41
	v_fmac_f32_e32 v169, 0x3e38aa3b, v67
	v_add_u32_e32 v67, 3, v165
	v_cmp_gt_u32_e64 s[22:23], s87, v67
	s_nop 1
	v_cndmask_b32_e64 v67, v221, v169, s[22:23]
	s_mov_b32 s22, 0xf149f2ca
	ds_read2_b32 v[168:169], v157 offset0:42 offset1:43
	s_waitcnt lgkmcnt(1)
	v_fmamk_f32 v68, v68, 0x3e38aa3b, v166
	v_add_u32_e32 v166, 8, v165
	v_max3_f32 v171, v65, s22, v67
	v_cmp_gt_u32_e64 s[22:23], s87, v166
	v_fmac_f32_e32 v167, 0x3e38aa3b, v69
	v_add_u32_e32 v69, 9, v165
	v_cndmask_b32_e64 v166, v221, v68, s[22:23]
	v_cmp_gt_u32_e64 s[22:23], s87, v69
	v_mov_b32_e32 v68, v166
	v_add_u32_e32 v166, 10, v165
	v_cndmask_b32_e64 v69, v221, v167, s[22:23]
	v_cmp_gt_u32_e64 s[22:23], s87, v166
	s_waitcnt lgkmcnt(0)
	v_fmamk_f32 v70, v70, 0x3e38aa3b, v168
	v_cndmask_b32_e64 v166, v221, v70, s[22:23]
	v_mov_b32_e32 v70, v166
	ds_read2_b32 v[166:167], v157 offset0:48 offset1:49
	v_fmac_f32_e32 v169, 0x3e38aa3b, v71
	v_add_u32_e32 v71, 11, v165
	v_cmp_gt_u32_e64 s[22:23], s87, v71
	s_nop 1
	v_cndmask_b32_e64 v71, v221, v169, s[22:23]
	ds_read2_b32 v[168:169], v157 offset0:50 offset1:51
	s_waitcnt lgkmcnt(1)
	v_fmamk_f32 v72, v72, 0x3e38aa3b, v166
	v_add_u32_e32 v166, 16, v165
	v_cmp_gt_u32_e64 s[22:23], s87, v166
	v_fmac_f32_e32 v167, 0x3e38aa3b, v73
	v_add_u32_e32 v73, 17, v165
	v_cndmask_b32_e64 v166, v221, v72, s[22:23]
	v_cmp_gt_u32_e64 s[22:23], s87, v73
	v_mov_b32_e32 v72, v166
	v_add_u32_e32 v166, 18, v165
	v_cndmask_b32_e64 v73, v221, v167, s[22:23]
	v_cmp_gt_u32_e64 s[22:23], s87, v166
	s_waitcnt lgkmcnt(0)
	v_fmamk_f32 v74, v74, 0x3e38aa3b, v168
	v_cndmask_b32_e64 v166, v221, v74, s[22:23]
	v_mov_b32_e32 v74, v166
	ds_read2_b32 v[166:167], v157 offset0:56 offset1:57
	v_fmac_f32_e32 v169, 0x3e38aa3b, v75
	v_add_u32_e32 v75, 19, v165
	v_cmp_gt_u32_e64 s[22:23], s87, v75
	s_nop 1
	v_cndmask_b32_e64 v75, v221, v169, s[22:23]
	v_mov_b32_e32 v168, v75
	s_waitcnt lgkmcnt(0)
; __device__ __forceinline__ int crow(int i, int h) { return (i & 3) + 8 * (i >> 2) + 4 * h; }
; __device__ __forceinline__ void attnA_unit(LAS unsigned char* lds, const Args& A, int unit) {
;     ...
;                 const bool edge = (i0 < 64) || (i0 + 96 > L);
;                 float mxp[2] = {-1e30f, -1e30f};
; #pragma unroll
;                 for (int kt = 0; kt < 5; ++kt)
; #pragma unroll
;                     for (int i = 0; i < 16; ++i) {
;                         const int cr = crow(i, 0);
;                         float v = S[kt][i] * QK_C + bl[32 * kt + cr + 4 * hh - ql + 32];
;                         if (edge) { const int kidx = i0 - 64 + 32 * kt + cr + 4 * hh; if (kidx < 0 || kidx >= L) v = -1e30f; }
;                         S[kt][i] = v; mxp[i & 1] = fmaxf(mxp[i & 1], v);
;                     }
;                 float mx = fmaxf(mxp[0], mxp[1]);
	v_fmamk_f32 v75, v76, 0x3e38aa3b, v166
	v_add_u32_e32 v76, 24, v165
	v_cmp_gt_u32_e64 s[22:23], s87, v76
	v_max_f32_e32 v170, 0xf149f2ca, v64
	v_max3_f32 v170, v170, v66, v68
	v_cndmask_b32_e64 v76, v221, v75, s[22:23]
	v_max3_f32 v171, v171, v69, v71
	v_max3_f32 v170, v170, v70, v72
	v_mov_b32_e32 v75, v76
	v_max3_f32 v169, v171, v73, v168
	v_max3_f32 v172, v170, v74, v75
	ds_read2_b32 v[170:171], v157 offset0:58 offset1:59
	v_add_u32_e32 v76, 25, v165
	v_cmp_gt_u32_e64 s[22:23], s87, v76
	v_fmac_f32_e32 v167, 0x3e38aa3b, v77
	s_nop 0
	v_cndmask_b32_e64 v76, v221, v167, s[22:23]
	ds_read2_b32 v[166:167], v157 offset0:64 offset1:65
	s_waitcnt lgkmcnt(1)
	v_fmamk_f32 v77, v78, 0x3e38aa3b, v170
	v_add_u32_e32 v78, 26, v165
	v_cmp_gt_u32_e64 s[22:23], s87, v78
	s_nop 1
	v_cndmask_b32_e64 v78, v221, v77, s[22:23]
	v_mov_b32_e32 v77, v78
	v_add_u32_e32 v78, 27, v165
	v_cmp_gt_u32_e64 s[22:23], s87, v78
	v_fmac_f32_e32 v171, 0x3e38aa3b, v79
	s_nop 0
	v_cndmask_b32_e64 v78, v221, v171, s[22:23]
	s_waitcnt lgkmcnt(0)
	v_fmamk_f32 v48, v48, 0x3e38aa3b, v166
	v_add_u32_e32 v166, 32, v165
	v_cmp_gt_u32_e64 s[22:23], s87, v166
	ds_read2_b32 v[170:171], v157 offset0:66 offset1:67
	v_fmac_f32_e32 v167, 0x3e38aa3b, v49
	v_add_u32_e32 v49, 33, v165
	v_cndmask_b32_e64 v166, v221, v48, s[22:23]
	v_cmp_gt_u32_e64 s[22:23], s87, v49
	v_mov_b32_e32 v48, v166
	v_add_u32_e32 v166, 34, v165
	v_cndmask_b32_e64 v49, v221, v167, s[22:23]
	v_cmp_gt_u32_e64 s[22:23], s87, v166
	s_waitcnt lgkmcnt(0)
	v_fmamk_f32 v50, v50, 0x3e38aa3b, v170
	v_cndmask_b32_e64 v166, v221, v50, s[22:23]
	v_mov_b32_e32 v50, v166
	ds_read2_b32 v[166:167], v157 offset0:72 offset1:73
	v_fmac_f32_e32 v171, 0x3e38aa3b, v51
	v_add_u32_e32 v51, 35, v165
	v_cmp_gt_u32_e64 s[22:23], s87, v51
	s_nop 1
	v_cndmask_b32_e64 v51, v221, v171, s[22:23]
	ds_read2_b32 v[170:171], v157 offset0:74 offset1:75
	s_waitcnt lgkmcnt(1)
	v_fmamk_f32 v52, v52, 0x3e38aa3b, v166
	v_add_u32_e32 v166, 40, v165
	v_cmp_gt_u32_e64 s[22:23], s87, v166
	v_fmac_f32_e32 v167, 0x3e38aa3b, v53
	v_add_u32_e32 v53, 41, v165
	v_cndmask_b32_e64 v166, v221, v52, s[22:23]
	v_cmp_gt_u32_e64 s[22:23], s87, v53
	v_mov_b32_e32 v52, v166
	v_add_u32_e32 v166, 42, v165
	v_cndmask_b32_e64 v53, v221, v167, s[22:23]
	v_cmp_gt_u32_e64 s[22:23], s87, v166
	s_waitcnt lgkmcnt(0)
	v_fmamk_f32 v54, v54, 0x3e38aa3b, v170
	v_cndmask_b32_e64 v166, v221, v54, s[22:23]
	v_mov_b32_e32 v54, v166
	ds_read2_b32 v[166:167], v157 offset0:80 offset1:81
	v_fmac_f32_e32 v171, 0x3e38aa3b, v55
	v_add_u32_e32 v55, 43, v165
	v_cmp_gt_u32_e64 s[22:23], s87, v55
	s_nop 1
	v_cndmask_b32_e64 v55, v221, v171, s[22:23]
	ds_read2_b32 v[170:171], v157 offset0:82 offset1:83
	s_waitcnt lgkmcnt(1)
	v_fmamk_f32 v56, v56, 0x3e38aa3b, v166
	v_add_u32_e32 v166, 48, v165
	v_cmp_gt_u32_e64 s[22:23], s87, v166
	v_fmac_f32_e32 v167, 0x3e38aa3b, v57
	v_add_u32_e32 v57, 49, v165
	v_cndmask_b32_e64 v166, v221, v56, s[22:23]
	v_cmp_gt_u32_e64 s[22:23], s87, v57
	v_mov_b32_e32 v56, v166
	v_add_u32_e32 v166, 50, v165
	v_cndmask_b32_e64 v57, v221, v167, s[22:23]
	v_cmp_gt_u32_e64 s[22:23], s87, v166
	s_waitcnt lgkmcnt(0)
	v_fmamk_f32 v58, v58, 0x3e38aa3b, v170
	v_cndmask_b32_e64 v166, v221, v58, s[22:23]
	v_mov_b32_e32 v58, v166
	ds_read2_b32 v[166:167], v157 offset0:88 offset1:89
	v_fmac_f32_e32 v171, 0x3e38aa3b, v59
	v_add_u32_e32 v59, 51, v165
	v_cmp_gt_u32_e64 s[22:23], s87, v59
	s_nop 1
	v_cndmask_b32_e64 v59, v221, v171, s[22:23]
	ds_read2_b32 v[170:171], v157 offset0:90 offset1:91
	s_waitcnt lgkmcnt(1)
	v_fmamk_f32 v60, v60, 0x3e38aa3b, v166
	v_add_u32_e32 v166, 56, v165
	v_cmp_gt_u32_e64 s[22:23], s87, v166
	v_fmac_f32_e32 v167, 0x3e38aa3b, v61
	v_add_u32_e32 v61, 57, v165
	v_cndmask_b32_e64 v166, v221, v60, s[22:23]
	v_cmp_gt_u32_e64 s[22:23], s87, v61
	s_nop 1
	v_cndmask_b32_e64 v61, v221, v167, s[22:23]
	v_add_u32_e32 v167, 58, v165
	v_max3_f32 v79, v169, v76, v78
	v_max3_f32 v169, v172, v77, v48
	v_cmp_gt_u32_e64 s[22:23], s87, v167
	v_max3_f32 v169, v169, v50, v52
	s_waitcnt lgkmcnt(0)
	v_fmamk_f32 v62, v62, 0x3e38aa3b, v170
	v_max3_f32 v169, v169, v54, v56
	v_mov_b32_e32 v60, v166
	v_cndmask_b32_e64 v167, v221, v62, s[22:23]
	v_max3_f32 v166, v169, v58, v60
	v_mov_b32_e32 v169, v167
	v_add_u32_e32 v62, 59, v165
	v_fmac_f32_e32 v171, 0x3e38aa3b, v63
	v_cmp_gt_u32_e64 s[22:23], s87, v62
	ds_read2_b32 v[62:63], v157 offset0:96 offset1:97
	s_nop 0
	v_cndmask_b32_e64 v167, v221, v171, s[22:23]
	v_mov_b32_e32 v208, v167
	v_max3_f32 v79, v79, v49, v51
	s_waitcnt lgkmcnt(0)
	v_fmamk_f32 v32, v32, 0x3e38aa3b, v62
	v_add_u32_e32 v62, 64, v165
	v_cmp_gt_u32_e64 s[22:23], s87, v62
	s_nop 1
	v_cndmask_b32_e64 v62, v221, v32, s[22:23]
	v_mov_b32_e32 v209, v62
	v_max3_f32 v32, v166, v169, v209
	ds_read2_b32 v[166:167], v157 offset0:98 offset1:99
	v_fmac_f32_e32 v63, 0x3e38aa3b, v33
	v_add_u32_e32 v33, 0x41, v165
	v_cmp_gt_u32_e64 s[22:23], s87, v33
	s_nop 1
	v_cndmask_b32_e64 v33, v221, v63, s[22:23]
	v_mov_b32_e32 v210, v33
	ds_read2_b32 v[62:63], v157 offset0:104 offset1:105
	s_waitcnt lgkmcnt(1)
	v_fmamk_f32 v33, v34, 0x3e38aa3b, v166
	v_add_u32_e32 v34, 0x42, v165
	v_cmp_gt_u32_e64 s[22:23], s87, v34
	s_nop 1
	v_cndmask_b32_e64 v34, v221, v33, s[22:23]
	v_mov_b32_e32 v33, v34
	v_add_u32_e32 v34, 0x43, v165
	v_cmp_gt_u32_e64 s[22:23], s87, v34
	v_fmac_f32_e32 v167, 0x3e38aa3b, v35
	s_waitcnt lgkmcnt(0)
	v_fmamk_f32 v35, v36, 0x3e38aa3b, v62
	v_add_u32_e32 v36, 0x48, v165
	v_cndmask_b32_e64 v34, v221, v167, s[22:23]
	v_cmp_gt_u32_e64 s[22:23], s87, v36
	s_nop 1
	v_cndmask_b32_e64 v36, v221, v35, s[22:23]
	ds_read2_b32 v[166:167], v157 offset0:106 offset1:107
	v_mov_b32_e32 v35, v36
	v_add_u32_e32 v36, 0x49, v165
	v_cmp_gt_u32_e64 s[22:23], s87, v36
	v_fmac_f32_e32 v63, 0x3e38aa3b, v37
	s_nop 0
	v_cndmask_b32_e64 v36, v221, v63, s[22:23]
	ds_read2_b32 v[62:63], v157 offset0:112 offset1:113
	s_waitcnt lgkmcnt(1)
; __device__ __forceinline__ int crow(int i, int h) { return (i & 3) + 8 * (i >> 2) + 4 * h; }
; __device__ __forceinline__ void attnA_unit(LAS unsigned char* lds, const Args& A, int unit) {
;     ...
;                 const bool edge = (i0 < 64) || (i0 + 96 > L);
;                 float mxp[2] = {-1e30f, -1e30f};
; #pragma unroll
;                 for (int kt = 0; kt < 5; ++kt)
; #pragma unroll
;                     for (int i = 0; i < 16; ++i) {
;                         const int cr = crow(i, 0);
;                         float v = S[kt][i] * QK_C + bl[32 * kt + cr + 4 * hh - ql + 32];
;                         if (edge) { const int kidx = i0 - 64 + 32 * kt + cr + 4 * hh; if (kidx < 0 || kidx >= L) v = -1e30f; }
;                         S[kt][i] = v; mxp[i & 1] = fmaxf(mxp[i & 1], v);
;                     }
;                 float mx = fmaxf(mxp[0], mxp[1]);
	v_fmamk_f32 v37, v38, 0x3e38aa3b, v166
	v_add_u32_e32 v38, 0x4a, v165
	v_cmp_gt_u32_e64 s[22:23], s87, v38
	s_nop 1
	v_cndmask_b32_e64 v38, v221, v37, s[22:23]
	v_mov_b32_e32 v37, v38
	v_add_u32_e32 v38, 0x4b, v165
	v_cmp_gt_u32_e64 s[22:23], s87, v38
	v_fmac_f32_e32 v167, 0x3e38aa3b, v39
	s_waitcnt lgkmcnt(0)
	v_fmamk_f32 v39, v40, 0x3e38aa3b, v62
	v_add_u32_e32 v40, 0x50, v165
	v_cndmask_b32_e64 v38, v221, v167, s[22:23]
	v_cmp_gt_u32_e64 s[22:23], s87, v40
	s_nop 1
	v_cndmask_b32_e64 v40, v221, v39, s[22:23]
	ds_read2_b32 v[166:167], v157 offset0:114 offset1:115
	v_mov_b32_e32 v39, v40
	v_add_u32_e32 v40, 0x51, v165
	v_cmp_gt_u32_e64 s[22:23], s87, v40
	v_fmac_f32_e32 v63, 0x3e38aa3b, v41
	s_nop 0
	v_cndmask_b32_e64 v40, v221, v63, s[22:23]
	ds_read2_b32 v[62:63], v157 offset0:120 offset1:121
	s_waitcnt lgkmcnt(1)
	v_fmamk_f32 v41, v42, 0x3e38aa3b, v166
	v_add_u32_e32 v42, 0x52, v165
	v_cmp_gt_u32_e64 s[22:23], s87, v42
	s_nop 1
	v_cndmask_b32_e64 v42, v221, v41, s[22:23]
	v_mov_b32_e32 v41, v42
	v_add_u32_e32 v42, 0x53, v165
	v_cmp_gt_u32_e64 s[22:23], s87, v42
	v_fmac_f32_e32 v167, 0x3e38aa3b, v43
	s_waitcnt lgkmcnt(0)
	v_fmamk_f32 v43, v44, 0x3e38aa3b, v62
	v_add_u32_e32 v44, 0x58, v165
	v_cndmask_b32_e64 v42, v221, v167, s[22:23]
	v_cmp_gt_u32_e64 s[22:23], s87, v44
	s_nop 1
	v_cndmask_b32_e64 v44, v221, v43, s[22:23]
	ds_read2_b32 v[166:167], v157 offset0:122 offset1:123
	v_mov_b32_e32 v43, v44
	v_add_u32_e32 v44, 0x59, v165
	v_cmp_gt_u32_e64 s[22:23], s87, v44
	v_fmac_f32_e32 v63, 0x3e38aa3b, v45
	s_nop 0
	v_cndmask_b32_e64 v44, v221, v63, s[22:23]
	ds_read2_b32 v[62:63], v157 offset0:128 offset1:129
	s_waitcnt lgkmcnt(1)
	v_fmamk_f32 v45, v46, 0x3e38aa3b, v166
	v_add_u32_e32 v46, 0x5a, v165
	v_cmp_gt_u32_e64 s[22:23], s87, v46
	s_nop 1
	v_cndmask_b32_e64 v46, v221, v45, s[22:23]
	v_mov_b32_e32 v45, v46
	v_add_u32_e32 v46, 0x5b, v165
	v_cmp_gt_u32_e64 s[22:23], s87, v46
	v_fmac_f32_e32 v167, 0x3e38aa3b, v47
	s_nop 0
	v_cndmask_b32_e64 v46, v221, v167, s[22:23]
	s_waitcnt lgkmcnt(0)
	v_fmamk_f32 v16, v16, 0x3e38aa3b, v62
	v_add_u32_e32 v62, 0x60, v165
	v_cmp_gt_u32_e64 s[22:23], s87, v62
	ds_read2_b32 v[166:167], v157 offset0:130 offset1:131
	v_fmac_f32_e32 v63, 0x3e38aa3b, v17
	v_add_u32_e32 v17, 0x61, v165
	v_cndmask_b32_e64 v62, v221, v16, s[22:23]
	v_cmp_gt_u32_e64 s[22:23], s87, v17
	v_max3_f32 v79, v79, v53, v55
	v_mov_b32_e32 v16, v62
	v_add_u32_e32 v62, 0x62, v165
	v_max3_f32 v79, v79, v57, v59
	v_cndmask_b32_e64 v17, v221, v63, s[22:23]
	v_cmp_gt_u32_e64 s[22:23], s87, v62
	v_max3_f32 v79, v79, v61, v208
	s_waitcnt lgkmcnt(0)
	v_fmamk_f32 v18, v18, 0x3e38aa3b, v166
	v_fmac_f32_e32 v167, 0x3e38aa3b, v19
	v_add_u32_e32 v19, 0x63, v165
	v_max3_f32 v79, v79, v210, v34
	v_cndmask_b32_e64 v62, v221, v18, s[22:23]
	v_cmp_gt_u32_e64 s[22:23], s87, v19
	v_max3_f32 v79, v79, v36, v38
	v_mov_b32_e32 v18, v62
	ds_read2_b32 v[62:63], v157 offset0:136 offset1:137
	v_max3_f32 v79, v79, v40, v42
	v_cndmask_b32_e64 v19, v221, v167, s[22:23]
	v_max3_f32 v47, v79, v44, v46
	v_max3_f32 v79, v47, v17, v19
	v_add_u32_e32 v47, 0x68, v165
	v_cmp_gt_u32_e64 s[22:23], s87, v47
	ds_read2_b32 v[166:167], v157 offset0:138 offset1:139
	s_waitcnt lgkmcnt(1)
	v_fmamk_f32 v20, v20, 0x3e38aa3b, v62
	v_fmac_f32_e32 v63, 0x3e38aa3b, v21
	v_add_u32_e32 v21, 0x69, v165
	v_cndmask_b32_e64 v47, v221, v20, s[22:23]
	v_cmp_gt_u32_e64 s[22:23], s87, v21
	s_nop 1
	v_cndmask_b32_e64 v21, v221, v63, s[22:23]
	v_mov_b32_e32 v20, v47
	v_mov_b32_e32 v47, v21
	s_waitcnt lgkmcnt(0)
	v_fmamk_f32 v21, v22, 0x3e38aa3b, v166
	v_add_u32_e32 v22, 0x6a, v165
	v_cmp_gt_u32_e64 s[22:23], s87, v22
	s_nop 1
	v_cndmask_b32_e64 v22, v221, v21, s[22:23]
	ds_read2_b32 v[62:63], v157 offset0:144 offset1:145
	v_mov_b32_e32 v211, v22
	v_add_u32_e32 v21, 0x6b, v165
	v_cmp_gt_u32_e64 s[22:23], s87, v21
	v_fmac_f32_e32 v167, 0x3e38aa3b, v23
	s_nop 0
	v_cndmask_b32_e64 v21, v221, v167, s[22:23]
	v_mov_b32_e32 v23, v21
	ds_read2_b32 v[166:167], v157 offset0:146 offset1:147
	s_waitcnt lgkmcnt(1)
	v_fmamk_f32 v22, v24, 0x3e38aa3b, v62
	v_add_u32_e32 v24, 0x70, v165
	v_cmp_gt_u32_e64 s[22:23], s87, v24
	s_nop 1
	v_cndmask_b32_e64 v24, v221, v22, s[22:23]
	v_mov_b32_e32 v22, v24
	v_add_u32_e32 v24, 0x71, v165
	v_cmp_gt_u32_e64 s[22:23], s87, v24
	v_fmac_f32_e32 v63, 0x3e38aa3b, v25
	s_waitcnt lgkmcnt(0)
	v_fmamk_f32 v25, v26, 0x3e38aa3b, v166
	v_add_u32_e32 v26, 0x72, v165
	v_cndmask_b32_e64 v24, v221, v63, s[22:23]
	v_cmp_gt_u32_e64 s[22:23], s87, v26
	s_nop 1
	v_cndmask_b32_e64 v26, v221, v25, s[22:23]
	v_mov_b32_e32 v25, v26
	v_add_u32_e32 v26, 0x73, v165
	ds_read2_b32 v[62:63], v157 offset0:152 offset1:153
	v_cmp_gt_u32_e64 s[22:23], s87, v26
	v_fmac_f32_e32 v167, 0x3e38aa3b, v27
	s_nop 0
	v_cndmask_b32_e64 v26, v221, v167, s[22:23]
	v_max3_f32 v21, v79, v47, v23
	v_mov_b32_e32 v27, v26
	v_add_u32_e32 v26, 0x78, v165
	v_max3_f32 v79, v21, v24, v27
	s_waitcnt lgkmcnt(0)
; __device__ __forceinline__ int crow(int i, int h) { return (i & 3) + 8 * (i >> 2) + 4 * h; }
; __device__ __forceinline__ void attnA_unit(LAS unsigned char* lds, const Args& A, int unit) {
;     ...
;                 const bool edge = (i0 < 64) || (i0 + 96 > L);
;                 float mxp[2] = {-1e30f, -1e30f};
; #pragma unroll
;                 for (int kt = 0; kt < 5; ++kt)
; #pragma unroll
;                     for (int i = 0; i < 16; ++i) {
;                         const int cr = crow(i, 0);
;                         float v = S[kt][i] * QK_C + bl[32 * kt + cr + 4 * hh - ql + 32];
;                         if (edge) { const int kidx = i0 - 64 + 32 * kt + cr + 4 * hh; if (kidx < 0 || kidx >= L) v = -1e30f; }
;                         S[kt][i] = v; mxp[i & 1] = fmaxf(mxp[i & 1], v);
;                     }
;                 float mx = fmaxf(mxp[0], mxp[1]);
	v_fmamk_f32 v21, v28, 0x3e38aa3b, v62
	v_cmp_gt_u32_e64 s[22:23], s87, v26
	v_fmac_f32_e32 v63, 0x3e38aa3b, v29
	ds_read2_b32 v[28:29], v157 offset0:154 offset1:155
	v_cndmask_b32_e64 v26, v221, v21, s[22:23]
	v_mov_b32_e32 v21, v26
	v_add_u32_e32 v26, 0x79, v165
	v_cmp_gt_u32_e64 s[22:23], s87, v26
	s_waitcnt lgkmcnt(0)
	v_fmamk_f32 v28, v30, 0x3e38aa3b, v28
	v_add_u32_e32 v30, 0x7a, v165
	v_cndmask_b32_e64 v26, v221, v63, s[22:23]
	v_cmp_gt_u32_e64 s[22:23], s87, v30
	s_nop 1
	v_cndmask_b32_e64 v30, v221, v28, s[22:23]
	v_mov_b32_e32 v28, v30
	v_add_u32_e32 v30, 0x7b, v165
	v_fmac_f32_e32 v29, 0x3e38aa3b, v31
	v_cmp_gt_u32_e64 s[22:23], s87, v30
	ds_read2_b32 v[30:31], v157 offset0:160 offset1:161
	v_max3_f32 v32, v32, v33, v35
	v_max3_f32 v32, v32, v37, v39
	v_cndmask_b32_e64 v62, v221, v29, s[22:23]
	s_waitcnt lgkmcnt(0)
	v_fmamk_f32 v0, v0, 0x3e38aa3b, v30
	v_add_u32_e32 v30, 0x80, v165
	v_cmp_gt_u32_e64 s[22:23], s87, v30
	v_max3_f32 v32, v32, v41, v43
	v_max3_f32 v32, v32, v45, v16
	v_cndmask_b32_e64 v30, v221, v0, s[22:23]
	v_max3_f32 v32, v32, v18, v20
	v_mov_b32_e32 v223, v30
	v_fmac_f32_e32 v31, 0x3e38aa3b, v1
	ds_read2_b32 v[0:1], v157 offset0:162 offset1:163
	v_max3_f32 v32, v32, v211, v22
	v_max3_f32 v32, v32, v25, v21
	v_max3_f32 v30, v32, v28, v223
	v_add_u32_e32 v32, 0x81, v165
	v_cmp_gt_u32_e64 s[22:23], s87, v32
	s_waitcnt lgkmcnt(0)
	v_fmamk_f32 v0, v2, 0x3e38aa3b, v0
	v_add_u32_e32 v2, 0x82, v165
	v_cndmask_b32_e64 v32, v221, v31, s[22:23]
	v_cmp_gt_u32_e64 s[22:23], s87, v2
	s_nop 1
	v_cndmask_b32_e64 v2, v221, v0, s[22:23]
	v_mov_b32_e32 v225, v2
	v_add_u32_e32 v0, 0x83, v165
	v_fmac_f32_e32 v1, 0x3e38aa3b, v3
	v_cmp_gt_u32_e64 s[22:23], s87, v0
	ds_read2_b32 v[2:3], v157 offset0:168 offset1:169
	s_nop 0
	v_cndmask_b32_e64 v0, v221, v1, s[22:23]
	v_mov_b32_e32 v227, v0
	v_add_u32_e32 v1, 0x88, v165
	v_cmp_gt_u32_e64 s[22:23], s87, v1
	s_waitcnt lgkmcnt(0)
	v_fmamk_f32 v0, v4, 0x3e38aa3b, v2
	v_cndmask_b32_e64 v1, v221, v0, s[22:23]
	v_add_u32_e32 v2, 0x89, v165
	v_mov_b32_e32 v228, v1
	ds_read2_b32 v[0:1], v157 offset0:170 offset1:171
	v_cmp_gt_u32_e64 s[22:23], s87, v2
	v_fmac_f32_e32 v3, 0x3e38aa3b, v5
	s_nop 0
	v_cndmask_b32_e64 v2, v221, v3, s[22:23]
	v_mov_b32_e32 v230, v2
	v_add_u32_e32 v2, 0x8a, v165
	v_cmp_gt_u32_e64 s[22:23], s87, v2
	s_waitcnt lgkmcnt(0)
	v_fmamk_f32 v0, v6, 0x3e38aa3b, v0
	v_cndmask_b32_e64 v2, v221, v0, s[22:23]
	v_mov_b32_e32 v232, v2
	v_add_u32_e32 v0, 0x8b, v165
	v_cmp_gt_u32_e64 s[22:23], s87, v0
	ds_read2_b32 v[2:3], v157 offset0:176 offset1:177
	v_fmac_f32_e32 v1, 0x3e38aa3b, v7
	v_cndmask_b32_e64 v0, v221, v1, s[22:23]
	v_mov_b32_e32 v233, v0
	v_add_u32_e32 v1, 0x90, v165
	v_cmp_gt_u32_e64 s[22:23], s87, v1
	s_waitcnt lgkmcnt(0)
	v_fmamk_f32 v0, v8, 0x3e38aa3b, v2
	v_cndmask_b32_e64 v1, v221, v0, s[22:23]
	v_add_u32_e32 v2, 0x91, v165
	v_mov_b32_e32 v231, v1
	ds_read2_b32 v[0:1], v157 offset0:178 offset1:179
	v_cmp_gt_u32_e64 s[22:23], s87, v2
	v_fmac_f32_e32 v3, 0x3e38aa3b, v9
	s_nop 0
	v_cndmask_b32_e64 v2, v221, v3, s[22:23]
	v_mov_b32_e32 v234, v2
	v_add_u32_e32 v2, 0x92, v165
	v_cmp_gt_u32_e64 s[22:23], s87, v2
	s_waitcnt lgkmcnt(0)
	v_fmamk_f32 v0, v10, 0x3e38aa3b, v0
	v_cndmask_b32_e64 v2, v221, v0, s[22:23]
	v_mov_b32_e32 v235, v2
	v_add_u32_e32 v0, 0x93, v165
	v_cmp_gt_u32_e64 s[22:23], s87, v0
	ds_read2_b32 v[2:3], v157 offset0:184 offset1:185
	v_fmac_f32_e32 v1, 0x3e38aa3b, v11
	v_cndmask_b32_e64 v0, v221, v1, s[22:23]
	v_mov_b32_e32 v236, v0
	v_add_u32_e32 v1, 0x98, v165
	v_cmp_gt_u32_e64 s[22:23], s87, v1
	s_waitcnt lgkmcnt(0)
	v_fmamk_f32 v0, v12, 0x3e38aa3b, v2
	v_max3_f32 v4, v30, v225, v228
	v_cndmask_b32_e64 v1, v221, v0, s[22:23]
	v_max3_f32 v4, v4, v232, v231
	v_mov_b32_e32 v237, v1
	v_max3_f32 v2, v4, v235, v237
	v_add_u32_e32 v4, 0x99, v165
	ds_read2_b32 v[0:1], v157 offset0:186 offset1:187
	v_cmp_gt_u32_e64 s[22:23], s87, v4
	v_fmac_f32_e32 v3, 0x3e38aa3b, v13
	s_nop 0
	v_cndmask_b32_e64 v4, v221, v3, s[22:23]
	v_mov_b32_e32 v240, v4
	v_add_u32_e32 v3, 0x9a, v165
	v_cmp_gt_u32_e64 s[22:23], s87, v3
	s_waitcnt lgkmcnt(0)
	v_fmamk_f32 v0, v14, 0x3e38aa3b, v0
	v_cndmask_b32_e64 v3, v221, v0, s[22:23]
	v_mov_b32_e32 v224, v62
	v_mov_b32_e32 v239, v3
	v_add_u32_e32 v0, 0x9b, v165
	v_max3_f32 v29, v79, v26, v224
	v_mov_b32_e32 v226, v32
	v_cmp_gt_u32_e64 s[22:23], s87, v0
	v_max3_f32 v29, v29, v226, v227
	v_fmac_f32_e32 v1, 0x3e38aa3b, v15
	v_max3_f32 v5, v29, v230, v233
	v_cndmask_b32_e64 v0, v221, v1, s[22:23]
	v_max3_f32 v5, v5, v234, v236
	v_mov_b32_e32 v241, v0
	v_max3_f32 v0, v5, v240, v241
	v_max3_f32 v0, v2, v239, v0
	s_branch .LmixA_join

.Lmixb_loop:
	v_mfma_f32_32x32x16_bf16 v[32:47], v[160:163], v[238:241], v[32:47]
	ds_read_b128 v[96:99], v172 offset:21504
	ds_read_b128 v[100:103], v172 offset:21536
	v_exp_f32_e32 v30, v30
	v_cvt_pk_bf16_f32 v244, v28, v29
	v_exp_f32_e32 v31, v31
	v_mfma_f32_32x32x16_bf16 v[48:63], v[164:167], v[238:241], v[48:63]
	v_mfma_f32_16x16x32_bf16 v[174:177], v[178:181], v[238:241], v[174:177]
	ds_read_b128 v[104:107], v172 offset:21568
	ds_read_b128 v[108:111], v172 offset:21600
	v_exp_f32_e32 v0, v0
	v_cvt_pk_bf16_f32 v245, v30, v31
	v_exp_f32_e32 v1, v1
	v_add_u32_e32 v214, 0x2000, v214
	global_load_dwordx4 v[152:155], v214, s[4:5]
	global_load_dwordx4 v[156:159], v214, s[6:7]
	v_mfma_f32_32x32x16_bf16 v[32:47], v[190:193], v[242:245], v[32:47]
	ds_read_b128 v[112:115], v172 offset:26112
	ds_read_b128 v[116:119], v172 offset:26144
	v_exp_f32_e32 v2, v2
	v_cvt_pk_bf16_f32 v246, v0, v1
	v_exp_f32_e32 v3, v3
	v_mfma_f32_32x32x16_bf16 v[48:63], v[194:197], v[242:245], v[48:63]
	v_mfma_f32_16x16x32_bf16 v[174:177], v[178:181], v[242:245], v[174:177]
	ds_read_b128 v[120:123], v172 offset:26176
	ds_read_b128 v[124:127], v172 offset:26208
	v_exp_f32_e32 v4, v4
	v_cvt_pk_bf16_f32 v247, v2, v3
	v_exp_f32_e32 v5, v5
	s_waitcnt lgkmcnt(4)
	v_mfma_f32_32x32x16_bf16 v[80:95], v[96:99], v[128:131], 0
	v_exp_f32_e32 v6, v6
	v_cvt_pk_bf16_f32 v248, v4, v5
	v_exp_f32_e32 v7, v7
	ds_read_b64_tr_b16 v[198:199], v182 offset:15360
	ds_read_b64_tr_b16 v[200:201], v182 offset:16896
	v_mfma_f32_32x32x16_bf16 v[80:95], v[100:103], v[132:135], v[80:95]
	v_exp_f32_e32 v8, v8
	v_cvt_pk_bf16_f32 v249, v6, v7
	v_exp_f32_e32 v9, v9
	ds_read_b64_tr_b16 v[202:203], v182 offset:15424
	ds_read_b64_tr_b16 v[204:205], v182 offset:16960
	v_mfma_f32_32x32x16_bf16 v[80:95], v[104:107], v[136:139], v[80:95]
	v_exp_f32_e32 v10, v10
	v_cvt_pk_bf16_f32 v250, v8, v9
	v_exp_f32_e32 v11, v11
	ds_read_b64_tr_b16 v[206:207], v182 offset:18432
	ds_read_b64_tr_b16 v[208:209], v182 offset:19968
	v_mfma_f32_32x32x16_bf16 v[80:95], v[108:111], v[140:143], v[80:95]
	v_exp_f32_e32 v12, v12
	v_cvt_pk_bf16_f32 v251, v10, v11
	v_exp_f32_e32 v13, v13
	ds_read_b64_tr_b16 v[234:235], v182 offset:18496
	ds_read_b64_tr_b16 v[236:237], v182 offset:20032
	s_waitcnt lgkmcnt(8)
	v_mfma_f32_32x32x16_bf16 v[64:79], v[112:115], v[128:131], 0
	v_exp_f32_e32 v14, v14
	v_cvt_pk_bf16_f32 v252, v12, v13
	v_exp_f32_e32 v15, v15
	ds_read_b64_tr_b16 v[160:161], v182 offset:30720
	ds_read_b64_tr_b16 v[162:163], v182 offset:32256
	v_mfma_f32_32x32x16_bf16 v[64:79], v[116:119], v[132:135], v[64:79]
	v_exp_f32_e32 v80, v80
	v_cvt_pk_bf16_f32 v253, v14, v15
	v_exp_f32_e32 v81, v81
	ds_read_b64_tr_b16 v[164:165], v182 offset:30784
	ds_read_b64_tr_b16 v[166:167], v182 offset:32320
	v_mfma_f32_32x32x16_bf16 v[64:79], v[120:123], v[136:139], v[64:79]
	v_exp_f32_e32 v82, v82
	v_cvt_pk_bf16_f32 v238, v80, v81
	v_exp_f32_e32 v83, v83
	ds_read_b64_tr_b16 v[190:191], v182 offset:33792
	ds_read_b64_tr_b16 v[192:193], v182 offset:35328
	v_mfma_f32_32x32x16_bf16 v[64:79], v[124:127], v[140:143], v[64:79]
	v_exp_f32_e32 v84, v84
	v_cvt_pk_bf16_f32 v239, v82, v83
	v_exp_f32_e32 v85, v85
	ds_read_b64_tr_b16 v[194:195], v182 offset:33856
	ds_read_b64_tr_b16 v[196:197], v182 offset:35392
	s_waitcnt lgkmcnt(8)
	v_mfma_f32_32x32x16_bf16 v[32:47], v[198:201], v[246:249], v[32:47]
	v_exp_f32_e32 v86, v86
	v_cvt_pk_bf16_f32 v240, v84, v85
	v_exp_f32_e32 v87, v87
	s_waitcnt vmcnt(2)
	ds_write_b128 v187, v[144:147]
	v_mfma_f32_32x32x16_bf16 v[48:63], v[202:205], v[246:249], v[48:63]
	v_mfma_f32_16x16x32_bf16 v[174:177], v[178:181], v[246:249], v[174:177]
	v_exp_f32_e32 v88, v88
	v_cvt_pk_bf16_f32 v241, v86, v87
	v_exp_f32_e32 v89, v89
	ds_write_b128 v189, v[148:151] offset:9216
	v_mfma_f32_32x32x16_bf16 v[32:47], v[206:209], v[250:253], v[32:47]
	v_exp_f32_e32 v90, v90
	v_cvt_pk_bf16_f32 v242, v88, v89
	v_exp_f32_e32 v91, v91
	v_mfma_f32_32x32x16_bf16 v[48:63], v[234:237], v[250:253], v[48:63]
	v_mfma_f32_16x16x32_bf16 v[174:177], v[178:181], v[250:253], v[174:177]
	v_exp_f32_e32 v92, v92
	v_cvt_pk_bf16_f32 v243, v90, v91
	v_exp_f32_e32 v93, v93
	s_waitcnt lgkmcnt(0)
	s_barrier
	v_mfma_f32_32x32x16_bf16 v[32:47], v[160:163], v[238:241], v[32:47]
	ds_read_b128 v[96:99], v173
	ds_read_b128 v[100:103], v173 offset:32
	v_exp_f32_e32 v94, v94
	v_cvt_pk_bf16_f32 v244, v92, v93
	v_exp_f32_e32 v95, v95
	v_mfma_f32_32x32x16_bf16 v[48:63], v[164:167], v[238:241], v[48:63]
	v_mfma_f32_16x16x32_bf16 v[174:177], v[178:181], v[238:241], v[174:177]
	ds_read_b128 v[104:107], v173 offset:64
	ds_read_b128 v[108:111], v173 offset:96
	v_exp_f32_e32 v64, v64
	v_cvt_pk_bf16_f32 v245, v94, v95
	v_exp_f32_e32 v65, v65
	v_add_u32_e32 v214, 0x2000, v214
	global_load_dwordx4 v[144:147], v214, s[4:5]
	global_load_dwordx4 v[148:151], v214, s[6:7]
	v_mfma_f32_32x32x16_bf16 v[32:47], v[190:193], v[242:245], v[32:47]
	ds_read_b128 v[112:115], v173 offset:4608
	ds_read_b128 v[116:119], v173 offset:4640
	v_exp_f32_e32 v66, v66
	v_cvt_pk_bf16_f32 v246, v64, v65
	v_exp_f32_e32 v67, v67
	v_mfma_f32_32x32x16_bf16 v[48:63], v[194:197], v[242:245], v[48:63]
	v_mfma_f32_16x16x32_bf16 v[174:177], v[178:181], v[242:245], v[174:177]
	ds_read_b128 v[120:123], v173 offset:4672
	ds_read_b128 v[124:127], v173 offset:4704
	v_exp_f32_e32 v68, v68
	v_cvt_pk_bf16_f32 v247, v66, v67
	v_exp_f32_e32 v69, v69
	s_waitcnt lgkmcnt(4)
	v_mfma_f32_32x32x16_bf16 v[16:31], v[96:99], v[128:131], 0
	v_exp_f32_e32 v70, v70
	v_cvt_pk_bf16_f32 v248, v68, v69
	v_exp_f32_e32 v71, v71
	ds_read_b64_tr_b16 v[198:199], v182 offset:36864
	ds_read_b64_tr_b16 v[200:201], v182 offset:38400
	v_mfma_f32_32x32x16_bf16 v[16:31], v[100:103], v[132:135], v[16:31]
	v_exp_f32_e32 v72, v72
	v_cvt_pk_bf16_f32 v249, v70, v71
	v_exp_f32_e32 v73, v73
	ds_read_b64_tr_b16 v[202:203], v182 offset:36928
	ds_read_b64_tr_b16 v[204:205], v182 offset:38464
	v_mfma_f32_32x32x16_bf16 v[16:31], v[104:107], v[136:139], v[16:31]
	v_exp_f32_e32 v74, v74
	v_cvt_pk_bf16_f32 v250, v72, v73
	v_exp_f32_e32 v75, v75
	ds_read_b64_tr_b16 v[206:207], v182 offset:39936
	ds_read_b64_tr_b16 v[208:209], v182 offset:41472
	v_mfma_f32_32x32x16_bf16 v[16:31], v[108:111], v[140:143], v[16:31]
	v_exp_f32_e32 v76, v76
	v_cvt_pk_bf16_f32 v251, v74, v75
	v_exp_f32_e32 v77, v77
	ds_read_b64_tr_b16 v[234:235], v182 offset:40000
	ds_read_b64_tr_b16 v[236:237], v182 offset:41536
	s_waitcnt lgkmcnt(8)
	v_mfma_f32_32x32x16_bf16 v[0:15], v[112:115], v[128:131], 0
	v_exp_f32_e32 v78, v78
	v_cvt_pk_bf16_f32 v252, v76, v77
	v_exp_f32_e32 v79, v79
	ds_read_b64_tr_b16 v[160:161], v183 offset:9216
	ds_read_b64_tr_b16 v[162:163], v183 offset:10752
	v_mfma_f32_32x32x16_bf16 v[0:15], v[116:119], v[132:135], v[0:15]
	v_exp_f32_e32 v16, v16
	v_cvt_pk_bf16_f32 v253, v78, v79
	v_exp_f32_e32 v17, v17
	ds_read_b64_tr_b16 v[164:165], v183 offset:9280
	ds_read_b64_tr_b16 v[166:167], v183 offset:10816
	v_mfma_f32_32x32x16_bf16 v[0:15], v[120:123], v[136:139], v[0:15]
	v_exp_f32_e32 v18, v18
	v_cvt_pk_bf16_f32 v238, v16, v17
	v_exp_f32_e32 v19, v19
	ds_read_b64_tr_b16 v[190:191], v183 offset:12288
	ds_read_b64_tr_b16 v[192:193], v183 offset:13824
	v_mfma_f32_32x32x16_bf16 v[0:15], v[124:127], v[140:143], v[0:15]
	v_exp_f32_e32 v20, v20
	v_cvt_pk_bf16_f32 v239, v18, v19
	v_exp_f32_e32 v21, v21
	ds_read_b64_tr_b16 v[194:195], v183 offset:12352
	ds_read_b64_tr_b16 v[196:197], v183 offset:13888
	s_waitcnt lgkmcnt(8)
	v_mfma_f32_32x32x16_bf16 v[32:47], v[198:201], v[246:249], v[32:47]
	v_exp_f32_e32 v22, v22
	v_cvt_pk_bf16_f32 v240, v20, v21
	v_exp_f32_e32 v23, v23
	s_waitcnt vmcnt(2)
	ds_write_b128 v187, v[152:155] offset:21504
	v_mfma_f32_32x32x16_bf16 v[48:63], v[202:205], v[246:249], v[48:63]
	v_mfma_f32_16x16x32_bf16 v[174:177], v[178:181], v[246:249], v[174:177]
	v_exp_f32_e32 v24, v24
	v_cvt_pk_bf16_f32 v241, v22, v23
	v_exp_f32_e32 v25, v25
	ds_write_b128 v189, v[156:159] offset:30720
	v_mfma_f32_32x32x16_bf16 v[32:47], v[206:209], v[250:253], v[32:47]
	v_exp_f32_e32 v26, v26
	v_cvt_pk_bf16_f32 v242, v24, v25
	v_exp_f32_e32 v27, v27
	v_mfma_f32_32x32x16_bf16 v[48:63], v[234:237], v[250:253], v[48:63]
	v_mfma_f32_16x16x32_bf16 v[174:177], v[178:181], v[250:253], v[174:177]
	v_exp_f32_e32 v28, v28
	v_cvt_pk_bf16_f32 v243, v26, v27
	v_exp_f32_e32 v29, v29
	s_waitcnt lgkmcnt(0)
	s_barrier
	v_mfma_f32_32x32x16_bf16 v[32:47], v[160:163], v[238:241], v[32:47]
	ds_read_b128 v[96:99], v173 offset:21504
	ds_read_b128 v[100:103], v173 offset:21536
	v_exp_f32_e32 v30, v30
	v_cvt_pk_bf16_f32 v244, v28, v29
	v_exp_f32_e32 v31, v31
	v_mfma_f32_32x32x16_bf16 v[48:63], v[164:167], v[238:241], v[48:63]
	v_mfma_f32_16x16x32_bf16 v[174:177], v[178:181], v[238:241], v[174:177]
	ds_read_b128 v[104:107], v173 offset:21568
	ds_read_b128 v[108:111], v173 offset:21600
	v_exp_f32_e32 v0, v0
	v_cvt_pk_bf16_f32 v245, v30, v31
	v_exp_f32_e32 v1, v1
	v_add_u32_e32 v214, 0x2000, v214
	global_load_dwordx4 v[152:155], v214, s[4:5]
	global_load_dwordx4 v[156:159], v214, s[6:7]
	v_mfma_f32_32x32x16_bf16 v[32:47], v[190:193], v[242:245], v[32:47]
	ds_read_b128 v[112:115], v173 offset:26112
	ds_read_b128 v[116:119], v173 offset:26144
	v_exp_f32_e32 v2, v2
	v_cvt_pk_bf16_f32 v246, v0, v1
	v_exp_f32_e32 v3, v3
	v_mfma_f32_32x32x16_bf16 v[48:63], v[194:197], v[242:245], v[48:63]
	v_mfma_f32_16x16x32_bf16 v[174:177], v[178:181], v[242:245], v[174:177]
	ds_read_b128 v[120:123], v173 offset:26176
	ds_read_b128 v[124:127], v173 offset:26208
	v_exp_f32_e32 v4, v4
	v_cvt_pk_bf16_f32 v247, v2, v3
	v_exp_f32_e32 v5, v5
	s_waitcnt lgkmcnt(4)
	v_mfma_f32_32x32x16_bf16 v[80:95], v[96:99], v[128:131], 0
	v_exp_f32_e32 v6, v6
	v_cvt_pk_bf16_f32 v248, v4, v5
	v_exp_f32_e32 v7, v7
	ds_read_b64_tr_b16 v[198:199], v183 offset:15360
	ds_read_b64_tr_b16 v[200:201], v183 offset:16896
	v_mfma_f32_32x32x16_bf16 v[80:95], v[100:103], v[132:135], v[80:95]
	v_exp_f32_e32 v8, v8
	v_cvt_pk_bf16_f32 v249, v6, v7
	v_exp_f32_e32 v9, v9
	ds_read_b64_tr_b16 v[202:203], v183 offset:15424
	ds_read_b64_tr_b16 v[204:205], v183 offset:16960
	v_mfma_f32_32x32x16_bf16 v[80:95], v[104:107], v[136:139], v[80:95]
	v_exp_f32_e32 v10, v10
	v_cvt_pk_bf16_f32 v250, v8, v9
	v_exp_f32_e32 v11, v11
	ds_read_b64_tr_b16 v[206:207], v183 offset:18432
	ds_read_b64_tr_b16 v[208:209], v183 offset:19968
	v_mfma_f32_32x32x16_bf16 v[80:95], v[108:111], v[140:143], v[80:95]
	v_exp_f32_e32 v12, v12
	v_cvt_pk_bf16_f32 v251, v10, v11
	v_exp_f32_e32 v13, v13
	ds_read_b64_tr_b16 v[234:235], v183 offset:18496
	ds_read_b64_tr_b16 v[236:237], v183 offset:20032
	s_waitcnt lgkmcnt(8)
	v_mfma_f32_32x32x16_bf16 v[64:79], v[112:115], v[128:131], 0
	v_exp_f32_e32 v14, v14
	v_cvt_pk_bf16_f32 v252, v12, v13
	v_exp_f32_e32 v15, v15
	ds_read_b64_tr_b16 v[160:161], v183 offset:30720
	ds_read_b64_tr_b16 v[162:163], v183 offset:32256
	v_mfma_f32_32x32x16_bf16 v[64:79], v[116:119], v[132:135], v[64:79]
	v_exp_f32_e32 v80, v80
	v_cvt_pk_bf16_f32 v253, v14, v15
	v_exp_f32_e32 v81, v81
	ds_read_b64_tr_b16 v[164:165], v183 offset:30784
	ds_read_b64_tr_b16 v[166:167], v183 offset:32320
	v_mfma_f32_32x32x16_bf16 v[64:79], v[120:123], v[136:139], v[64:79]
	v_exp_f32_e32 v82, v82
	v_cvt_pk_bf16_f32 v238, v80, v81
	v_exp_f32_e32 v83, v83
	ds_read_b64_tr_b16 v[190:191], v183 offset:33792
	ds_read_b64_tr_b16 v[192:193], v183 offset:35328
	v_mfma_f32_32x32x16_bf16 v[64:79], v[124:127], v[140:143], v[64:79]
	v_exp_f32_e32 v84, v84
	v_cvt_pk_bf16_f32 v239, v82, v83
	v_exp_f32_e32 v85, v85
	ds_read_b64_tr_b16 v[194:195], v183 offset:33856
	ds_read_b64_tr_b16 v[196:197], v183 offset:35392
	s_waitcnt lgkmcnt(8)
	v_mfma_f32_32x32x16_bf16 v[32:47], v[198:201], v[246:249], v[32:47]
	v_exp_f32_e32 v86, v86
	v_cvt_pk_bf16_f32 v240, v84, v85
	v_exp_f32_e32 v87, v87
	s_waitcnt vmcnt(2)
	ds_write_b128 v186, v[144:147]
	v_mfma_f32_32x32x16_bf16 v[48:63], v[202:205], v[246:249], v[48:63]
	v_mfma_f32_16x16x32_bf16 v[174:177], v[178:181], v[246:249], v[174:177]
	v_exp_f32_e32 v88, v88
	v_cvt_pk_bf16_f32 v241, v86, v87
	v_exp_f32_e32 v89, v89
	ds_write_b128 v188, v[148:151] offset:9216
	v_mfma_f32_32x32x16_bf16 v[32:47], v[206:209], v[250:253], v[32:47]
	v_exp_f32_e32 v90, v90
	v_cvt_pk_bf16_f32 v242, v88, v89
	v_exp_f32_e32 v91, v91
	v_mfma_f32_32x32x16_bf16 v[48:63], v[234:237], v[250:253], v[48:63]
	v_mfma_f32_16x16x32_bf16 v[174:177], v[178:181], v[250:253], v[174:177]
	v_exp_f32_e32 v92, v92
	v_cvt_pk_bf16_f32 v243, v90, v91
	v_exp_f32_e32 v93, v93
	s_waitcnt lgkmcnt(0)
	s_barrier
	v_mfma_f32_32x32x16_bf16 v[32:47], v[160:163], v[238:241], v[32:47]
	ds_read_b128 v[96:99], v172
	ds_read_b128 v[100:103], v172 offset:32
	v_exp_f32_e32 v94, v94
	v_cvt_pk_bf16_f32 v244, v92, v93
	v_exp_f32_e32 v95, v95
	v_mfma_f32_32x32x16_bf16 v[48:63], v[164:167], v[238:241], v[48:63]
	v_mfma_f32_16x16x32_bf16 v[174:177], v[178:181], v[238:241], v[174:177]
	ds_read_b128 v[104:107], v172 offset:64
	ds_read_b128 v[108:111], v172 offset:96
	v_exp_f32_e32 v64, v64
	v_cvt_pk_bf16_f32 v245, v94, v95
	v_exp_f32_e32 v65, v65
	v_add_u32_e32 v214, 0x2000, v214
	global_load_dwordx4 v[144:147], v214, s[4:5]
	global_load_dwordx4 v[148:151], v214, s[6:7]
	v_mfma_f32_32x32x16_bf16 v[32:47], v[190:193], v[242:245], v[32:47]
	ds_read_b128 v[112:115], v172 offset:4608
	ds_read_b128 v[116:119], v172 offset:4640
	v_exp_f32_e32 v66, v66
	v_cvt_pk_bf16_f32 v246, v64, v65
	v_exp_f32_e32 v67, v67
	v_mfma_f32_32x32x16_bf16 v[48:63], v[194:197], v[242:245], v[48:63]
	v_mfma_f32_16x16x32_bf16 v[174:177], v[178:181], v[242:245], v[174:177]
	ds_read_b128 v[120:123], v172 offset:4672
	ds_read_b128 v[124:127], v172 offset:4704
	v_exp_f32_e32 v68, v68
	v_cvt_pk_bf16_f32 v247, v66, v67
	v_exp_f32_e32 v69, v69
	s_waitcnt lgkmcnt(4)
	v_mfma_f32_32x32x16_bf16 v[16:31], v[96:99], v[128:131], 0
	v_exp_f32_e32 v70, v70
	v_cvt_pk_bf16_f32 v248, v68, v69
	v_exp_f32_e32 v71, v71
	ds_read_b64_tr_b16 v[198:199], v183 offset:36864
	ds_read_b64_tr_b16 v[200:201], v183 offset:38400
	v_mfma_f32_32x32x16_bf16 v[16:31], v[100:103], v[132:135], v[16:31]
	v_exp_f32_e32 v72, v72
	v_cvt_pk_bf16_f32 v249, v70, v71
	v_exp_f32_e32 v73, v73
	ds_read_b64_tr_b16 v[202:203], v183 offset:36928
	ds_read_b64_tr_b16 v[204:205], v183 offset:38464
	v_mfma_f32_32x32x16_bf16 v[16:31], v[104:107], v[136:139], v[16:31]
	v_exp_f32_e32 v74, v74
	v_cvt_pk_bf16_f32 v250, v72, v73
	v_exp_f32_e32 v75, v75
	ds_read_b64_tr_b16 v[206:207], v183 offset:39936
	ds_read_b64_tr_b16 v[208:209], v183 offset:41472
	v_mfma_f32_32x32x16_bf16 v[16:31], v[108:111], v[140:143], v[16:31]
	v_exp_f32_e32 v76, v76
	v_cvt_pk_bf16_f32 v251, v74, v75
	v_exp_f32_e32 v77, v77
	ds_read_b64_tr_b16 v[234:235], v183 offset:40000
	ds_read_b64_tr_b16 v[236:237], v183 offset:41536
	s_waitcnt lgkmcnt(8)
	v_mfma_f32_32x32x16_bf16 v[0:15], v[112:115], v[128:131], 0
	v_exp_f32_e32 v78, v78
	v_cvt_pk_bf16_f32 v252, v76, v77
	v_exp_f32_e32 v79, v79
	ds_read_b64_tr_b16 v[160:161], v182 offset:9216
	ds_read_b64_tr_b16 v[162:163], v182 offset:10752
	v_mfma_f32_32x32x16_bf16 v[0:15], v[116:119], v[132:135], v[0:15]
	v_exp_f32_e32 v16, v16
	v_cvt_pk_bf16_f32 v253, v78, v79
	v_exp_f32_e32 v17, v17
	ds_read_b64_tr_b16 v[164:165], v182 offset:9280
	ds_read_b64_tr_b16 v[166:167], v182 offset:10816
	v_mfma_f32_32x32x16_bf16 v[0:15], v[120:123], v[136:139], v[0:15]
	v_exp_f32_e32 v18, v18
	v_cvt_pk_bf16_f32 v238, v16, v17
	v_exp_f32_e32 v19, v19
	ds_read_b64_tr_b16 v[190:191], v182 offset:12288
	ds_read_b64_tr_b16 v[192:193], v182 offset:13824
	v_mfma_f32_32x32x16_bf16 v[0:15], v[124:127], v[140:143], v[0:15]
	v_exp_f32_e32 v20, v20
	v_cvt_pk_bf16_f32 v239, v18, v19
	v_exp_f32_e32 v21, v21
	ds_read_b64_tr_b16 v[194:195], v182 offset:12352
	ds_read_b64_tr_b16 v[196:197], v182 offset:13888
	s_waitcnt lgkmcnt(8)
	v_mfma_f32_32x32x16_bf16 v[32:47], v[198:201], v[246:249], v[32:47]
	v_exp_f32_e32 v22, v22
	v_cvt_pk_bf16_f32 v240, v20, v21
	v_exp_f32_e32 v23, v23
	s_waitcnt vmcnt(2)
	ds_write_b128 v186, v[152:155] offset:21504
	v_mfma_f32_32x32x16_bf16 v[48:63], v[202:205], v[246:249], v[48:63]
	v_mfma_f32_16x16x32_bf16 v[174:177], v[178:181], v[246:249], v[174:177]
	v_exp_f32_e32 v24, v24
	v_cvt_pk_bf16_f32 v241, v22, v23
	v_exp_f32_e32 v25, v25
	ds_write_b128 v188, v[156:159] offset:30720
	v_mfma_f32_32x32x16_bf16 v[32:47], v[206:209], v[250:253], v[32:47]
	v_exp_f32_e32 v26, v26
	v_cvt_pk_bf16_f32 v242, v24, v25
	v_exp_f32_e32 v27, v27
	v_mfma_f32_32x32x16_bf16 v[48:63], v[234:237], v[250:253], v[48:63]
	v_mfma_f32_16x16x32_bf16 v[174:177], v[178:181], v[250:253], v[174:177]
	v_exp_f32_e32 v28, v28
	v_cvt_pk_bf16_f32 v243, v26, v27
	v_exp_f32_e32 v29, v29
	s_add_i32 s11, s11, -1
	s_cmp_lg_u32 s11, 0
	s_waitcnt lgkmcnt(0)
	s_barrier
	s_cbranch_scc1 .Lmixb_loop
	v_mfma_f32_32x32x16_bf16 v[32:47], v[160:163], v[238:241], v[32:47]
	ds_read_b128 v[96:99], v172 offset:21504
	ds_read_b128 v[100:103], v172 offset:21536
	v_exp_f32_e32 v30, v30
	v_cvt_pk_bf16_f32 v244, v28, v29
	v_exp_f32_e32 v31, v31
	v_mfma_f32_32x32x16_bf16 v[48:63], v[164:167], v[238:241], v[48:63]
	v_mfma_f32_16x16x32_bf16 v[174:177], v[178:181], v[238:241], v[174:177]
	ds_read_b128 v[104:107], v172 offset:21568
	ds_read_b128 v[108:111], v172 offset:21600
	v_exp_f32_e32 v0, v0
	v_cvt_pk_bf16_f32 v245, v30, v31
	v_exp_f32_e32 v1, v1
	v_add_u32_e32 v214, 0x2000, v214
	global_load_dwordx4 v[152:155], v214, s[4:5]
	global_load_dwordx4 v[156:159], v214, s[6:7]
	v_mfma_f32_32x32x16_bf16 v[32:47], v[190:193], v[242:245], v[32:47]
	ds_read_b128 v[112:115], v172 offset:26112
	ds_read_b128 v[116:119], v172 offset:26144
	v_exp_f32_e32 v2, v2
	v_cvt_pk_bf16_f32 v246, v0, v1
	v_exp_f32_e32 v3, v3
	v_mfma_f32_32x32x16_bf16 v[48:63], v[194:197], v[242:245], v[48:63]
	v_mfma_f32_16x16x32_bf16 v[174:177], v[178:181], v[242:245], v[174:177]
	ds_read_b128 v[120:123], v172 offset:26176
	ds_read_b128 v[124:127], v172 offset:26208
	v_exp_f32_e32 v4, v4
	v_cvt_pk_bf16_f32 v247, v2, v3
	v_exp_f32_e32 v5, v5
	s_waitcnt lgkmcnt(4)
	v_mfma_f32_32x32x16_bf16 v[80:95], v[96:99], v[128:131], 0
	v_exp_f32_e32 v6, v6
	v_cvt_pk_bf16_f32 v248, v4, v5
	v_exp_f32_e32 v7, v7
	ds_read_b64_tr_b16 v[198:199], v182 offset:15360
	ds_read_b64_tr_b16 v[200:201], v182 offset:16896
	v_mfma_f32_32x32x16_bf16 v[80:95], v[100:103], v[132:135], v[80:95]
	v_exp_f32_e32 v8, v8
	v_cvt_pk_bf16_f32 v249, v6, v7
	v_exp_f32_e32 v9, v9
	ds_read_b64_tr_b16 v[202:203], v182 offset:15424
	ds_read_b64_tr_b16 v[204:205], v182 offset:16960
	v_mfma_f32_32x32x16_bf16 v[80:95], v[104:107], v[136:139], v[80:95]
	v_exp_f32_e32 v10, v10
	v_cvt_pk_bf16_f32 v250, v8, v9
	v_exp_f32_e32 v11, v11
	ds_read_b64_tr_b16 v[206:207], v182 offset:18432
	ds_read_b64_tr_b16 v[208:209], v182 offset:19968
	v_mfma_f32_32x32x16_bf16 v[80:95], v[108:111], v[140:143], v[80:95]
	v_exp_f32_e32 v12, v12
	v_cvt_pk_bf16_f32 v251, v10, v11
	v_exp_f32_e32 v13, v13
	ds_read_b64_tr_b16 v[234:235], v182 offset:18496
	ds_read_b64_tr_b16 v[236:237], v182 offset:20032
	s_waitcnt lgkmcnt(8)
	v_mfma_f32_32x32x16_bf16 v[64:79], v[112:115], v[128:131], 0
	v_exp_f32_e32 v14, v14
	v_cvt_pk_bf16_f32 v252, v12, v13
	v_exp_f32_e32 v15, v15
	ds_read_b64_tr_b16 v[160:161], v182 offset:30720
	ds_read_b64_tr_b16 v[162:163], v182 offset:32256
	v_mfma_f32_32x32x16_bf16 v[64:79], v[116:119], v[132:135], v[64:79]
	v_exp_f32_e32 v80, v80
	v_cvt_pk_bf16_f32 v253, v14, v15
	v_exp_f32_e32 v81, v81
	ds_read_b64_tr_b16 v[164:165], v182 offset:30784
	ds_read_b64_tr_b16 v[166:167], v182 offset:32320
	v_mfma_f32_32x32x16_bf16 v[64:79], v[120:123], v[136:139], v[64:79]
	v_exp_f32_e32 v82, v82
	v_cvt_pk_bf16_f32 v238, v80, v81
	v_exp_f32_e32 v83, v83
	ds_read_b64_tr_b16 v[190:191], v182 offset:33792
	ds_read_b64_tr_b16 v[192:193], v182 offset:35328
	v_mfma_f32_32x32x16_bf16 v[64:79], v[124:127], v[140:143], v[64:79]
	v_exp_f32_e32 v84, v84
	v_cvt_pk_bf16_f32 v239, v82, v83
	v_exp_f32_e32 v85, v85
	ds_read_b64_tr_b16 v[194:195], v182 offset:33856
	ds_read_b64_tr_b16 v[196:197], v182 offset:35392
	s_waitcnt lgkmcnt(8)
	v_mfma_f32_32x32x16_bf16 v[32:47], v[198:201], v[246:249], v[32:47]
	v_exp_f32_e32 v86, v86
	v_cvt_pk_bf16_f32 v240, v84, v85
	v_exp_f32_e32 v87, v87
	s_waitcnt vmcnt(2)
	ds_write_b128 v187, v[144:147]
	v_mfma_f32_32x32x16_bf16 v[48:63], v[202:205], v[246:249], v[48:63]
	v_mfma_f32_16x16x32_bf16 v[174:177], v[178:181], v[246:249], v[174:177]
	v_exp_f32_e32 v88, v88
	v_cvt_pk_bf16_f32 v241, v86, v87
	v_exp_f32_e32 v89, v89
	ds_write_b128 v189, v[148:151] offset:9216
	v_mfma_f32_32x32x16_bf16 v[32:47], v[206:209], v[250:253], v[32:47]
	v_exp_f32_e32 v90, v90
	v_cvt_pk_bf16_f32 v242, v88, v89
	v_exp_f32_e32 v91, v91
	v_mfma_f32_32x32x16_bf16 v[48:63], v[234:237], v[250:253], v[48:63]
	v_mfma_f32_16x16x32_bf16 v[174:177], v[178:181], v[250:253], v[174:177]
	v_exp_f32_e32 v92, v92
	v_cvt_pk_bf16_f32 v243, v90, v91
	v_exp_f32_e32 v93, v93
	s_waitcnt lgkmcnt(0)
	s_barrier
	v_mfma_f32_32x32x16_bf16 v[32:47], v[160:163], v[238:241], v[32:47]
	ds_read_b128 v[96:99], v173
	ds_read_b128 v[100:103], v173 offset:32
	v_exp_f32_e32 v94, v94
	v_cvt_pk_bf16_f32 v244, v92, v93
	v_exp_f32_e32 v95, v95
	v_mfma_f32_32x32x16_bf16 v[48:63], v[164:167], v[238:241], v[48:63]
	v_mfma_f32_16x16x32_bf16 v[174:177], v[178:181], v[238:241], v[174:177]
	ds_read_b128 v[104:107], v173 offset:64
	ds_read_b128 v[108:111], v173 offset:96
	v_exp_f32_e32 v64, v64
	v_cvt_pk_bf16_f32 v245, v94, v95
	v_exp_f32_e32 v65, v65
	s_nop 0
	v_mfma_f32_32x32x16_bf16 v[32:47], v[190:193], v[242:245], v[32:47]
	ds_read_b128 v[112:115], v173 offset:4608
	ds_read_b128 v[116:119], v173 offset:4640
	v_exp_f32_e32 v66, v66
	v_cvt_pk_bf16_f32 v246, v64, v65
	v_exp_f32_e32 v67, v67
	v_mfma_f32_32x32x16_bf16 v[48:63], v[194:197], v[242:245], v[48:63]
	v_mfma_f32_16x16x32_bf16 v[174:177], v[178:181], v[242:245], v[174:177]
	ds_read_b128 v[120:123], v173 offset:4672
	ds_read_b128 v[124:127], v173 offset:4704
	v_exp_f32_e32 v68, v68
	v_cvt_pk_bf16_f32 v247, v66, v67
	v_exp_f32_e32 v69, v69
	s_waitcnt lgkmcnt(4)
	v_mfma_f32_32x32x16_bf16 v[16:31], v[96:99], v[128:131], 0
	v_exp_f32_e32 v70, v70
	v_cvt_pk_bf16_f32 v248, v68, v69
	v_exp_f32_e32 v71, v71
	ds_read_b64_tr_b16 v[198:199], v182 offset:36864
	ds_read_b64_tr_b16 v[200:201], v182 offset:38400
	v_mfma_f32_32x32x16_bf16 v[16:31], v[100:103], v[132:135], v[16:31]
	v_exp_f32_e32 v72, v72
	v_cvt_pk_bf16_f32 v249, v70, v71
	v_exp_f32_e32 v73, v73
	ds_read_b64_tr_b16 v[202:203], v182 offset:36928
	ds_read_b64_tr_b16 v[204:205], v182 offset:38464
	v_mfma_f32_32x32x16_bf16 v[16:31], v[104:107], v[136:139], v[16:31]
	v_exp_f32_e32 v74, v74
	v_cvt_pk_bf16_f32 v250, v72, v73
	v_exp_f32_e32 v75, v75
	ds_read_b64_tr_b16 v[206:207], v182 offset:39936
	ds_read_b64_tr_b16 v[208:209], v182 offset:41472
	v_mfma_f32_32x32x16_bf16 v[16:31], v[108:111], v[140:143], v[16:31]
	v_exp_f32_e32 v76, v76
	v_cvt_pk_bf16_f32 v251, v74, v75
	v_exp_f32_e32 v77, v77
	ds_read_b64_tr_b16 v[234:235], v182 offset:40000
	ds_read_b64_tr_b16 v[236:237], v182 offset:41536
	s_waitcnt lgkmcnt(8)
	v_mfma_f32_32x32x16_bf16 v[0:15], v[112:115], v[128:131], 0
	v_exp_f32_e32 v78, v78
	v_cvt_pk_bf16_f32 v252, v76, v77
	v_exp_f32_e32 v79, v79
	ds_read_b64_tr_b16 v[160:161], v183 offset:9216
	ds_read_b64_tr_b16 v[162:163], v183 offset:10752
	v_mfma_f32_32x32x16_bf16 v[0:15], v[116:119], v[132:135], v[0:15]
	v_exp_f32_e32 v16, v16
	v_cvt_pk_bf16_f32 v253, v78, v79
	v_exp_f32_e32 v17, v17
	ds_read_b64_tr_b16 v[164:165], v183 offset:9280
	ds_read_b64_tr_b16 v[166:167], v183 offset:10816
	v_mfma_f32_32x32x16_bf16 v[0:15], v[120:123], v[136:139], v[0:15]
	v_exp_f32_e32 v18, v18
	v_cvt_pk_bf16_f32 v238, v16, v17
	v_exp_f32_e32 v19, v19
	ds_read_b64_tr_b16 v[190:191], v183 offset:12288
	ds_read_b64_tr_b16 v[192:193], v183 offset:13824
	v_mfma_f32_32x32x16_bf16 v[0:15], v[124:127], v[140:143], v[0:15]
	v_exp_f32_e32 v20, v20
	v_cvt_pk_bf16_f32 v239, v18, v19
	v_exp_f32_e32 v21, v21
	ds_read_b64_tr_b16 v[194:195], v183 offset:12352
	ds_read_b64_tr_b16 v[196:197], v183 offset:13888
	s_waitcnt lgkmcnt(8)
	v_mfma_f32_32x32x16_bf16 v[32:47], v[198:201], v[246:249], v[32:47]
	v_exp_f32_e32 v22, v22
	v_cvt_pk_bf16_f32 v240, v20, v21
	v_exp_f32_e32 v23, v23
	s_waitcnt vmcnt(0)
	ds_write_b128 v187, v[152:155] offset:21504
	v_mfma_f32_32x32x16_bf16 v[48:63], v[202:205], v[246:249], v[48:63]
	v_mfma_f32_16x16x32_bf16 v[174:177], v[178:181], v[246:249], v[174:177]
	v_exp_f32_e32 v24, v24
	v_cvt_pk_bf16_f32 v241, v22, v23
	v_exp_f32_e32 v25, v25
	ds_write_b128 v189, v[156:159] offset:30720
	v_mfma_f32_32x32x16_bf16 v[32:47], v[206:209], v[250:253], v[32:47]
	v_exp_f32_e32 v26, v26
	v_cvt_pk_bf16_f32 v242, v24, v25
	v_exp_f32_e32 v27, v27
	v_mfma_f32_32x32x16_bf16 v[48:63], v[234:237], v[250:253], v[48:63]
	v_mfma_f32_16x16x32_bf16 v[174:177], v[178:181], v[250:253], v[174:177]
	v_exp_f32_e32 v28, v28
	v_cvt_pk_bf16_f32 v243, v26, v27
	v_exp_f32_e32 v29, v29
	s_waitcnt lgkmcnt(0)
	s_barrier
	v_mfma_f32_32x32x16_bf16 v[32:47], v[160:163], v[238:241], v[32:47]
	ds_read_b128 v[96:99], v173 offset:21504
	ds_read_b128 v[100:103], v173 offset:21536
	v_exp_f32_e32 v30, v30
	v_cvt_pk_bf16_f32 v244, v28, v29
	v_exp_f32_e32 v31, v31
	v_mfma_f32_32x32x16_bf16 v[48:63], v[164:167], v[238:241], v[48:63]
	v_mfma_f32_16x16x32_bf16 v[174:177], v[178:181], v[238:241], v[174:177]
	ds_read_b128 v[104:107], v173 offset:21568
	ds_read_b128 v[108:111], v173 offset:21600
	v_exp_f32_e32 v0, v0
	v_cvt_pk_bf16_f32 v245, v30, v31
	v_exp_f32_e32 v1, v1
	s_nop 0
	v_mfma_f32_32x32x16_bf16 v[32:47], v[190:193], v[242:245], v[32:47]
	ds_read_b128 v[112:115], v173 offset:26112
	ds_read_b128 v[116:119], v173 offset:26144
	v_exp_f32_e32 v2, v2
	v_cvt_pk_bf16_f32 v246, v0, v1
	v_exp_f32_e32 v3, v3
	v_mfma_f32_32x32x16_bf16 v[48:63], v[194:197], v[242:245], v[48:63]
	v_mfma_f32_16x16x32_bf16 v[174:177], v[178:181], v[242:245], v[174:177]
	ds_read_b128 v[120:123], v173 offset:26176
	ds_read_b128 v[124:127], v173 offset:26208
	v_exp_f32_e32 v4, v4
	v_cvt_pk_bf16_f32 v247, v2, v3
	v_exp_f32_e32 v5, v5
	s_waitcnt lgkmcnt(4)
	v_mfma_f32_32x32x16_bf16 v[80:95], v[96:99], v[128:131], 0
	v_exp_f32_e32 v6, v6
	v_cvt_pk_bf16_f32 v248, v4, v5
	v_exp_f32_e32 v7, v7
	ds_read_b64_tr_b16 v[198:199], v183 offset:15360
	ds_read_b64_tr_b16 v[200:201], v183 offset:16896
	v_mfma_f32_32x32x16_bf16 v[80:95], v[100:103], v[132:135], v[80:95]
	v_exp_f32_e32 v8, v8
	v_cvt_pk_bf16_f32 v249, v6, v7
	v_exp_f32_e32 v9, v9
	ds_read_b64_tr_b16 v[202:203], v183 offset:15424
	ds_read_b64_tr_b16 v[204:205], v183 offset:16960
	v_mfma_f32_32x32x16_bf16 v[80:95], v[104:107], v[136:139], v[80:95]
	v_exp_f32_e32 v10, v10
	v_cvt_pk_bf16_f32 v250, v8, v9
	v_exp_f32_e32 v11, v11
	ds_read_b64_tr_b16 v[206:207], v183 offset:18432
	ds_read_b64_tr_b16 v[208:209], v183 offset:19968
	v_mfma_f32_32x32x16_bf16 v[80:95], v[108:111], v[140:143], v[80:95]
	v_exp_f32_e32 v12, v12
	v_cvt_pk_bf16_f32 v251, v10, v11
	v_exp_f32_e32 v13, v13
	ds_read_b64_tr_b16 v[234:235], v183 offset:18496
	ds_read_b64_tr_b16 v[236:237], v183 offset:20032
	s_waitcnt lgkmcnt(8)
	v_mfma_f32_32x32x16_bf16 v[64:79], v[112:115], v[128:131], 0
	v_exp_f32_e32 v14, v14
	v_cvt_pk_bf16_f32 v252, v12, v13
	v_exp_f32_e32 v15, v15
	ds_read_b64_tr_b16 v[160:161], v183 offset:30720
	ds_read_b64_tr_b16 v[162:163], v183 offset:32256
	v_mfma_f32_32x32x16_bf16 v[64:79], v[116:119], v[132:135], v[64:79]
	v_exp_f32_e32 v80, v80
	v_cvt_pk_bf16_f32 v253, v14, v15
	v_exp_f32_e32 v81, v81
	ds_read_b64_tr_b16 v[164:165], v183 offset:30784
	ds_read_b64_tr_b16 v[166:167], v183 offset:32320
	v_mfma_f32_32x32x16_bf16 v[64:79], v[120:123], v[136:139], v[64:79]
	v_exp_f32_e32 v82, v82
	v_cvt_pk_bf16_f32 v238, v80, v81
	v_exp_f32_e32 v83, v83
	ds_read_b64_tr_b16 v[190:191], v183 offset:33792
	ds_read_b64_tr_b16 v[192:193], v183 offset:35328
	v_mfma_f32_32x32x16_bf16 v[64:79], v[124:127], v[140:143], v[64:79]
	v_exp_f32_e32 v84, v84
	v_cvt_pk_bf16_f32 v239, v82, v83
	v_exp_f32_e32 v85, v85
	ds_read_b64_tr_b16 v[194:195], v183 offset:33856
	ds_read_b64_tr_b16 v[196:197], v183 offset:35392
	s_waitcnt lgkmcnt(8)
	v_mfma_f32_32x32x16_bf16 v[32:47], v[198:201], v[246:249], v[32:47]
	v_exp_f32_e32 v86, v86
	v_cvt_pk_bf16_f32 v240, v84, v85
	v_exp_f32_e32 v87, v87
	v_mfma_f32_32x32x16_bf16 v[48:63], v[202:205], v[246:249], v[48:63]
	v_mfma_f32_16x16x32_bf16 v[174:177], v[178:181], v[246:249], v[174:177]
	v_exp_f32_e32 v88, v88
	v_cvt_pk_bf16_f32 v241, v86, v87
	v_exp_f32_e32 v89, v89
	v_mfma_f32_32x32x16_bf16 v[32:47], v[206:209], v[250:253], v[32:47]
	v_exp_f32_e32 v90, v90
	v_cvt_pk_bf16_f32 v242, v88, v89
	v_exp_f32_e32 v91, v91
	v_mfma_f32_32x32x16_bf16 v[48:63], v[234:237], v[250:253], v[48:63]
	v_mfma_f32_16x16x32_bf16 v[174:177], v[178:181], v[250:253], v[174:177]
	v_exp_f32_e32 v92, v92
	v_cvt_pk_bf16_f32 v243, v90, v91
	v_exp_f32_e32 v93, v93
	s_waitcnt lgkmcnt(0)
	s_barrier
	v_mfma_f32_32x32x16_bf16 v[32:47], v[160:163], v[238:241], v[32:47]
	v_exp_f32_e32 v94, v94
	v_cvt_pk_bf16_f32 v244, v92, v93
	v_exp_f32_e32 v95, v95
	v_mfma_f32_32x32x16_bf16 v[48:63], v[164:167], v[238:241], v[48:63]
	v_mfma_f32_16x16x32_bf16 v[174:177], v[178:181], v[238:241], v[174:177]
	v_exp_f32_e32 v64, v64
	v_cvt_pk_bf16_f32 v245, v94, v95
	v_exp_f32_e32 v65, v65
	s_nop 0
	v_mfma_f32_32x32x16_bf16 v[32:47], v[190:193], v[242:245], v[32:47]
	v_exp_f32_e32 v66, v66
	v_cvt_pk_bf16_f32 v246, v64, v65
	v_exp_f32_e32 v67, v67
	v_mfma_f32_32x32x16_bf16 v[48:63], v[194:197], v[242:245], v[48:63]
	v_mfma_f32_16x16x32_bf16 v[174:177], v[178:181], v[242:245], v[174:177]
	v_exp_f32_e32 v68, v68
	v_cvt_pk_bf16_f32 v247, v66, v67
	v_exp_f32_e32 v69, v69
	v_exp_f32_e32 v70, v70
	v_cvt_pk_bf16_f32 v248, v68, v69
	v_exp_f32_e32 v71, v71
	ds_read_b64_tr_b16 v[198:199], v183 offset:36864
	ds_read_b64_tr_b16 v[200:201], v183 offset:38400
	v_exp_f32_e32 v72, v72
	v_cvt_pk_bf16_f32 v249, v70, v71
	v_exp_f32_e32 v73, v73
	ds_read_b64_tr_b16 v[202:203], v183 offset:36928
	ds_read_b64_tr_b16 v[204:205], v183 offset:38464
	v_exp_f32_e32 v74, v74
	v_cvt_pk_bf16_f32 v250, v72, v73
	v_exp_f32_e32 v75, v75
	ds_read_b64_tr_b16 v[206:207], v183 offset:39936
	ds_read_b64_tr_b16 v[208:209], v183 offset:41472
	v_exp_f32_e32 v76, v76
	v_cvt_pk_bf16_f32 v251, v74, v75
	v_exp_f32_e32 v77, v77
	ds_read_b64_tr_b16 v[234:235], v183 offset:40000
	ds_read_b64_tr_b16 v[236:237], v183 offset:41536
	v_exp_f32_e32 v78, v78
	v_cvt_pk_bf16_f32 v252, v76, v77
	v_exp_f32_e32 v79, v79
	s_nop 0
	v_cvt_pk_bf16_f32 v253, v78, v79
	s_waitcnt lgkmcnt(0)
	v_mfma_f32_32x32x16_bf16 v[32:47], v[198:201], v[246:249], v[32:47]
	v_mfma_f32_32x32x16_bf16 v[48:63], v[202:205], v[246:249], v[48:63]
	v_mfma_f32_16x16x32_bf16 v[174:177], v[178:181], v[246:249], v[174:177]
	v_mfma_f32_32x32x16_bf16 v[32:47], v[206:209], v[250:253], v[32:47]
	v_mfma_f32_32x32x16_bf16 v[48:63], v[234:237], v[250:253], v[48:63]
	v_mfma_f32_16x16x32_bf16 v[174:177], v[178:181], v[250:253], v[174:177]
	s_nop 7
	v_and_b32_e32 v214, 15, v217
	v_lshlrev_b32_e32 v214, 2, v214
	v_and_b32_e32 v219, 16, v217
	ds_bpermute_b32 v215, v214, v174
	ds_bpermute_b32 v218, v214, v175
	v_cmp_ne_u32_e32 vcc, 0, v219
	s_waitcnt lgkmcnt(0)
	s_nop 1
	v_cndmask_b32_e32 v174, v215, v218, vcc
	v_mul_f32_e32 v174, 0.5, v174
	v_mov_b32_e32 v175, 0
	v_mov_b32_e32 v176, 0
	v_mov_b32_e32 v177, 0
	v_mov_b32_e32 v233, 0
	s_branch .LBB0_275
